# RWKV ring: consumed counters dropped (implied by the landed counters), poll reads one counter vector
# speedup vs baseline: 1.0154x; 1.0154x over previous
; #define RW_LANDED(WN, XN, KN, VN) asm volatile("s_waitcnt lgkmcnt(0)" : "+v"(WN), "+v"(XN), "+v"(KN), "+v"(VN) :: "memory")
; #define RW_DMA4(B) RW_DMA_ONLY(B); RW_DMA_ONLY((B) + 1); RW_DMA_ONLY((B) + 2); RW_DMA_ONLY((B) + 3)
; template <int DIR>
; DEVINL void rwkv_scan_dir(const Params& p, int task, int lane, int wave) {
;   const int b = (task >> 8) & 1, head = (task >> 4) & 15, rg = task & 15;
;   const int seg = lane & 15, rl = lane >> 4, row = rg * 4 + rl;
;   constexpr int DIST = 24;
;   constexpr int WOFS = DIR ? 8 : 0;
;   const char* recbase = p.ws + O_REC + ((long)(b * 16 + head) * 4096) * 1024 + lane * 16;
;   const unsigned ring_lds = (unsigned)(unsigned long)(__attribute__((address_space(3))) char*)(dynsmem + wave * 32768);
;   const unsigned ring_u = __builtin_amdgcn_readfirstlane(ring_lds);
;   const unsigned a_seg = ring_lds + seg * 64;
;   const unsigned a_v = ring_lds + (row >> 2) * 64 + 48 + (row & 3) * 2;
;   u16* yo = (u16*)(p.ws + (DIR ? O_YB : O_YSUM)) + ((long)b * 4096) * 1024 + head * 64 + row;
;   float s0 = 0.f, s1 = 0.f, s2 = 0.f, s3 = 0.f;
;   float ykeep = 0.f;
;   const char* recdir = recbase + (DIR ? (long)4095 * 1024 : 0);
;     ...
;   u32x2 WvA, WvB; u32x4 XA, XB, KrA, KrB; unsigned vhA, vhB;
;   RW_DMA4(0); RW_DMA4(4); RW_DMA4(8); RW_DMA4(12); RW_DMA4(16); RW_DMA4(20);
;   RW_READ(0, WvA, XA, KrA, vhA, 23);
;   RW_LANDED(WvA, XA, KrA, vhA);
;   float ypart = 0.f;
.Lrw_task:
	s_cmp_ge_u32 s7, 0x400
	s_cbranch_scc1 .Lrw_done
	s_and_b32 s24, s7, 15
	s_bfe_u32 s26, s7, 0x40004
	s_bfe_u32 s32, s7, 0x10008
	s_lshr_b32 s36, s7, 9
	s_lshl_b32 s3, s32, 4
	s_add_u32 s3, s3, s26
	s_lshl_b32 s3, s3, 22
	s_add_u32 s10, s92, s3
	s_addc_u32 s11, s93, 0
	s_add_u32 s10, s10, 0xf400000
	s_addc_u32 s11, s11, 0
	s_lshl_b32 s3, s32, 23
	s_lshl_b32 s37, s26, 7
	s_add_u32 s3, s3, s37
	s_add_u32 s12, s92, s3
	s_addc_u32 s13, s93, 0
	s_lshl_b32 s3, s24, 3
	v_lshl_add_u32 v8, v4, 1, s3
	s_lshl_b32 s37, s24, 4
	s_lshl_b32 s39, s6, 12
	s_cmp_lg_u32 s36, 0
	s_cbranch_scc1 .Lrw_bwd
	s_add_u32 s12, s12, 0x2000000
	s_addc_u32 s13, s13, 0
	v_lshl_add_u32 v8, v3, 11, v8
	s_add_u32 s10, s10, s39
	s_addc_u32 s11, s11, 0
	s_mov_b32 s40, s39
	s_mov_b32 s41, 0
	v_lshlrev_b32_e32 v6, 4, v3
	s_add_u32 s3, s37, 0x300
	v_lshl_add_u32 v7, v4, 1, s3
	s_add_u32 s3, s40, s41
	s_and_b32 s3, s3, 0x1ffff
	s_add_u32 s3, s3, 16
	s_mov_b32 m0, s3
	s_nop 0
	global_load_lds_dwordx4 v5, s[10:11] offset:0
	global_load_lds_dwordx4 v5, s[10:11] offset:1024
	global_load_lds_dwordx4 v5, s[10:11] offset:2048
	global_load_lds_dwordx4 v5, s[10:11] offset:3072
	s_add_u32 s10, s10, 0x4000
	s_addc_u32 s11, s11, 0
	s_add_u32 s41, s41, 0x4000
	s_and_b32 s41, s41, 0x1ffff
	s_add_u32 s3, s40, s41
	s_and_b32 s3, s3, 0x1ffff
	s_add_u32 s3, s3, 16
	s_mov_b32 m0, s3
	s_nop 0
	global_load_lds_dwordx4 v5, s[10:11] offset:0
	global_load_lds_dwordx4 v5, s[10:11] offset:1024
	global_load_lds_dwordx4 v5, s[10:11] offset:2048
	global_load_lds_dwordx4 v5, s[10:11] offset:3072
	s_add_u32 s10, s10, 0x4000
	s_addc_u32 s11, s11, 0
	s_add_u32 s41, s41, 0x4000
	s_and_b32 s41, s41, 0x1ffff
	s_add_u32 s3, s40, s41
	s_and_b32 s3, s3, 0x1ffff
	s_add_u32 s3, s3, 16
	s_mov_b32 m0, s3
	s_nop 0
	global_load_lds_dwordx4 v5, s[10:11] offset:0
	global_load_lds_dwordx4 v5, s[10:11] offset:1024
	global_load_lds_dwordx4 v5, s[10:11] offset:2048
	global_load_lds_dwordx4 v5, s[10:11] offset:3072
	s_add_u32 s10, s10, 0x4000
	s_addc_u32 s11, s11, 0
	s_add_u32 s41, s41, 0x4000
	s_and_b32 s41, s41, 0x1ffff
	s_waitcnt vmcnt(0)
	v_mov_b32_e32 v10, 0
	v_mov_b32_e32 v11, 0
	v_mov_b32_e32 v12, 0
	v_mov_b32_e32 v13, 0
	s_mov_b32 s14, 0
	s_add_u32 s3, s15, 3
	v_mov_b32_e32 v69, s3
	ds_write_b32 v23, v69
	s_add_u32 s43, s15, 2
	s_mov_b32 s42, 0
.Lrw_poll_d0p:
	ds_read_b128 v[100:103], v9
	s_waitcnt lgkmcnt(0)
.Lrw_test_d0p:
	v_min3_u32 v100, v100, v101, v102
	v_min_u32_e32 v100, v100, v103
	s_nop 0
	v_readfirstlane_b32 s24, v100
	s_nop 0
	s_cmp_ge_u32 s24, s43
	s_cbranch_scc1 .Lrw_ready_d0p
	s_sleep 1
	s_add_u32 s42, s42, 1
	s_cmp_lt_u32 s42, 0x400
	s_cbranch_scc1 .Lrw_poll_d0p

; template <int DIR>
; DEVINL void rwkv_scan_dir(const Params& p, int task, int lane, int wave) {
;     ...
; #pragma unroll 1
;   for (int st = 0; st < 4096; st += 32) {
;     RW_STEP(0, WvA, XA, KrA, vhA, WvB, XB, KrB, vhB);
.Lrw_nofull_d0:
	s_waitcnt vmcnt(1)
	s_add_u32 s3, s15, 3
	v_mov_b32_e32 v69, s3
	ds_write_b32 v23, v69
	s_add_u32 s43, s15, 2
	s_mov_b32 s42, 0
	s_branch .Lrw_test_d0

.Lrw_skip_d0:
	ds_read_b64 v[84:85], v6 offset:3088
	ds_read_b128 v[86:89], v6 offset:3344
	ds_read_b128 v[90:93], v6 offset:3600
	ds_read_u16 v94, v7 offset:3088
	v_fma_mix_f32 v14, v10, v38, 0 op_sel:[0,0,0] op_sel_hi:[0,1,0]
	v_fma_mix_f32 v48, v10, v32, 0 op_sel:[0,0,0] op_sel_hi:[0,1,0]
	v_fma_mix_f32 v14, v11, v38, v14 op_sel:[0,1,0] op_sel_hi:[0,1,0]
	v_fma_mix_f32 v48, v11, v32, v48 op_sel:[0,1,0] op_sel_hi:[0,1,0]
	v_fma_mix_f32 v14, v12, v39, v14 op_sel:[0,0,0] op_sel_hi:[0,1,0]
	v_fma_mix_f32 v48, v12, v33, v48 op_sel:[0,0,0] op_sel_hi:[0,1,0]
	v_fma_mix_f32 v14, v13, v39, v14 op_sel:[0,1,0] op_sel_hi:[0,1,0]
	v_fma_mix_f32 v16, v10, v36, 0 op_sel:[0,0,0] op_sel_hi:[0,1,0]
	v_fma_mix_f32 v17, v11, v36, 0 op_sel:[0,1,0] op_sel_hi:[0,1,0]
	v_add_f32_dpp v20, v14, v14 quad_perm:[1,0,3,2] row_mask:0xf bank_mask:0xf bound_ctrl:1
	v_fma_mix_f32 v48, v13, v33, v48 op_sel:[0,1,0] op_sel_hi:[0,1,0]
	v_fma_mix_f32 v18, v12, v37, 0 op_sel:[0,0,0] op_sel_hi:[0,1,0]
	v_add_f32_dpp v20, v20, v20 quad_perm:[2,3,0,1] row_mask:0xf bank_mask:0xf bound_ctrl:1
	v_fma_mix_f32 v19, v13, v37, 0 op_sel:[0,1,0] op_sel_hi:[0,1,0]
	v_fma_mix_f32 v16, v46, v42, v16 op_sel:[0,0,0] op_sel_hi:[1,1,0]
	v_add_f32_dpp v20, v20, v20 row_half_mirror row_mask:0xf bank_mask:0xf bound_ctrl:1
	v_fma_mix_f32 v17, v46, v42, v17 op_sel:[0,1,0] op_sel_hi:[1,1,0]
	v_fma_mix_f32 v18, v46, v43, v18 op_sel:[0,0,0] op_sel_hi:[1,1,0]
	v_add_f32_dpp v20, v20, v20 row_mirror row_mask:0xf bank_mask:0xf bound_ctrl:1
	v_fma_mix_f32 v19, v46, v43, v19 op_sel:[0,1,0] op_sel_hi:[1,1,0]
	v_fma_mix_f32 v10, v20, v40, v16 op_sel:[0,0,0] op_sel_hi:[0,1,0]
	v_fma_mix_f32 v11, v20, v40, v17 op_sel:[0,1,0] op_sel_hi:[0,1,0]
	v_fma_mix_f32 v12, v20, v41, v18 op_sel:[0,0,0] op_sel_hi:[0,1,0]
	v_fma_mix_f32 v13, v20, v41, v19 op_sel:[0,1,0] op_sel_hi:[0,1,0]
	s_waitcnt lgkmcnt(4)
	ds_read_b64 v[24:25], v6 offset:4112
	ds_read_b128 v[26:29], v6 offset:4368
	ds_read_b128 v[30:33], v6 offset:4624
	ds_read_u16 v34, v7 offset:4112
	v_fma_mix_f32 v14, v10, v74, 0 op_sel:[0,0,0] op_sel_hi:[0,1,0]
	v_fma_mix_f32 v49, v10, v44, 0 op_sel:[0,0,0] op_sel_hi:[0,1,0]
	v_fma_mix_f32 v14, v11, v74, v14 op_sel:[0,1,0] op_sel_hi:[0,1,0]
	v_fma_mix_f32 v49, v11, v44, v49 op_sel:[0,1,0] op_sel_hi:[0,1,0]
	v_fma_mix_f32 v14, v12, v75, v14 op_sel:[0,0,0] op_sel_hi:[0,1,0]
	v_fma_mix_f32 v49, v12, v45, v49 op_sel:[0,0,0] op_sel_hi:[0,1,0]
	v_fma_mix_f32 v14, v13, v75, v14 op_sel:[0,1,0] op_sel_hi:[0,1,0]
	v_fma_mix_f32 v16, v10, v72, 0 op_sel:[0,0,0] op_sel_hi:[0,1,0]
	v_fma_mix_f32 v17, v11, v72, 0 op_sel:[0,1,0] op_sel_hi:[0,1,0]
	v_add_f32_dpp v20, v14, v14 quad_perm:[1,0,3,2] row_mask:0xf bank_mask:0xf bound_ctrl:1
	v_fma_mix_f32 v49, v13, v45, v49 op_sel:[0,1,0] op_sel_hi:[0,1,0]
	v_fma_mix_f32 v18, v12, v73, 0 op_sel:[0,0,0] op_sel_hi:[0,1,0]
	v_add_f32_dpp v20, v20, v20 quad_perm:[2,3,0,1] row_mask:0xf bank_mask:0xf bound_ctrl:1
	v_fma_mix_f32 v19, v13, v73, 0 op_sel:[0,1,0] op_sel_hi:[0,1,0]
	v_fma_mix_f32 v16, v82, v78, v16 op_sel:[0,0,0] op_sel_hi:[1,1,0]
	v_add_f32_dpp v20, v20, v20 row_half_mirror row_mask:0xf bank_mask:0xf bound_ctrl:1
	v_fma_mix_f32 v17, v82, v78, v17 op_sel:[0,1,0] op_sel_hi:[1,1,0]
	v_fma_mix_f32 v18, v82, v79, v18 op_sel:[0,0,0] op_sel_hi:[1,1,0]
	v_add_f32_dpp v20, v20, v20 row_mirror row_mask:0xf bank_mask:0xf bound_ctrl:1
	v_fma_mix_f32 v19, v82, v79, v19 op_sel:[0,1,0] op_sel_hi:[1,1,0]
	v_fma_mix_f32 v10, v20, v76, v16 op_sel:[0,0,0] op_sel_hi:[0,1,0]
	v_fma_mix_f32 v11, v20, v76, v17 op_sel:[0,1,0] op_sel_hi:[0,1,0]
	v_fma_mix_f32 v12, v20, v77, v18 op_sel:[0,0,0] op_sel_hi:[0,1,0]
	v_fma_mix_f32 v13, v20, v77, v19 op_sel:[0,1,0] op_sel_hi:[0,1,0]
	s_waitcnt lgkmcnt(4)
	ds_read_b64 v[36:37], v6 offset:5136
	ds_read_b128 v[38:41], v6 offset:5392
	ds_read_b128 v[42:45], v6 offset:5648
	ds_read_u16 v46, v7 offset:5136
	v_fma_mix_f32 v14, v10, v86, 0 op_sel:[0,0,0] op_sel_hi:[0,1,0]
	v_fma_mix_f32 v50, v10, v80, 0 op_sel:[0,0,0] op_sel_hi:[0,1,0]
	v_fma_mix_f32 v14, v11, v86, v14 op_sel:[0,1,0] op_sel_hi:[0,1,0]
	v_fma_mix_f32 v50, v11, v80, v50 op_sel:[0,1,0] op_sel_hi:[0,1,0]
	v_fma_mix_f32 v14, v12, v87, v14 op_sel:[0,0,0] op_sel_hi:[0,1,0]
	v_fma_mix_f32 v50, v12, v81, v50 op_sel:[0,0,0] op_sel_hi:[0,1,0]
	v_fma_mix_f32 v14, v13, v87, v14 op_sel:[0,1,0] op_sel_hi:[0,1,0]
	v_fma_mix_f32 v16, v10, v84, 0 op_sel:[0,0,0] op_sel_hi:[0,1,0]
	v_fma_mix_f32 v17, v11, v84, 0 op_sel:[0,1,0] op_sel_hi:[0,1,0]
	v_add_f32_dpp v20, v14, v14 quad_perm:[1,0,3,2] row_mask:0xf bank_mask:0xf bound_ctrl:1
	v_fma_mix_f32 v50, v13, v81, v50 op_sel:[0,1,0] op_sel_hi:[0,1,0]
	v_fma_mix_f32 v18, v12, v85, 0 op_sel:[0,0,0] op_sel_hi:[0,1,0]
	v_add_f32_dpp v20, v20, v20 quad_perm:[2,3,0,1] row_mask:0xf bank_mask:0xf bound_ctrl:1
	v_fma_mix_f32 v19, v13, v85, 0 op_sel:[0,1,0] op_sel_hi:[0,1,0]
	v_fma_mix_f32 v16, v94, v90, v16 op_sel:[0,0,0] op_sel_hi:[1,1,0]
	v_add_f32_dpp v20, v20, v20 row_half_mirror row_mask:0xf bank_mask:0xf bound_ctrl:1
	v_fma_mix_f32 v17, v94, v90, v17 op_sel:[0,1,0] op_sel_hi:[1,1,0]
	v_fma_mix_f32 v18, v94, v91, v18 op_sel:[0,0,0] op_sel_hi:[1,1,0]
	v_add_f32_dpp v20, v20, v20 row_mirror row_mask:0xf bank_mask:0xf bound_ctrl:1
	v_fma_mix_f32 v19, v94, v91, v19 op_sel:[0,1,0] op_sel_hi:[1,1,0]
	v_fma_mix_f32 v10, v20, v88, v16 op_sel:[0,0,0] op_sel_hi:[0,1,0]
	v_fma_mix_f32 v11, v20, v88, v17 op_sel:[0,1,0] op_sel_hi:[0,1,0]
	v_fma_mix_f32 v12, v20, v89, v18 op_sel:[0,0,0] op_sel_hi:[0,1,0]
	v_fma_mix_f32 v13, v20, v89, v19 op_sel:[0,1,0] op_sel_hi:[0,1,0]
	s_waitcnt lgkmcnt(4)
	ds_read_b64 v[72:73], v6 offset:6160
	ds_read_b128 v[74:77], v6 offset:6416
	ds_read_b128 v[78:81], v6 offset:6672
	ds_read_u16 v82, v7 offset:6160
	v_fma_mix_f32 v14, v10, v26, 0 op_sel:[0,0,0] op_sel_hi:[0,1,0]
	v_fma_mix_f32 v51, v10, v92, 0 op_sel:[0,0,0] op_sel_hi:[0,1,0]
	v_fma_mix_f32 v14, v11, v26, v14 op_sel:[0,1,0] op_sel_hi:[0,1,0]
	v_fma_mix_f32 v51, v11, v92, v51 op_sel:[0,1,0] op_sel_hi:[0,1,0]
	v_fma_mix_f32 v14, v12, v27, v14 op_sel:[0,0,0] op_sel_hi:[0,1,0]
	v_fma_mix_f32 v51, v12, v93, v51 op_sel:[0,0,0] op_sel_hi:[0,1,0]
	v_fma_mix_f32 v14, v13, v27, v14 op_sel:[0,1,0] op_sel_hi:[0,1,0]
	v_fma_mix_f32 v16, v10, v24, 0 op_sel:[0,0,0] op_sel_hi:[0,1,0]
	v_fma_mix_f32 v17, v11, v24, 0 op_sel:[0,1,0] op_sel_hi:[0,1,0]
	v_add_f32_dpp v20, v14, v14 quad_perm:[1,0,3,2] row_mask:0xf bank_mask:0xf bound_ctrl:1
	v_fma_mix_f32 v51, v13, v93, v51 op_sel:[0,1,0] op_sel_hi:[0,1,0]
	v_fma_mix_f32 v18, v12, v25, 0 op_sel:[0,0,0] op_sel_hi:[0,1,0]
	v_add_f32_dpp v20, v20, v20 quad_perm:[2,3,0,1] row_mask:0xf bank_mask:0xf bound_ctrl:1
	v_fma_mix_f32 v19, v13, v25, 0 op_sel:[0,1,0] op_sel_hi:[0,1,0]
	v_fma_mix_f32 v16, v34, v30, v16 op_sel:[0,0,0] op_sel_hi:[1,1,0]
	v_add_f32_dpp v20, v20, v20 row_half_mirror row_mask:0xf bank_mask:0xf bound_ctrl:1
	v_fma_mix_f32 v17, v34, v30, v17 op_sel:[0,1,0] op_sel_hi:[1,1,0]
	v_fma_mix_f32 v18, v34, v31, v18 op_sel:[0,0,0] op_sel_hi:[1,1,0]
	v_add_f32_dpp v20, v20, v20 row_mirror row_mask:0xf bank_mask:0xf bound_ctrl:1
	v_fma_mix_f32 v19, v34, v31, v19 op_sel:[0,1,0] op_sel_hi:[1,1,0]
	v_fma_mix_f32 v10, v20, v28, v16 op_sel:[0,0,0] op_sel_hi:[0,1,0]
	v_fma_mix_f32 v11, v20, v28, v17 op_sel:[0,1,0] op_sel_hi:[0,1,0]
	v_fma_mix_f32 v12, v20, v29, v18 op_sel:[0,0,0] op_sel_hi:[0,1,0]
	v_fma_mix_f32 v13, v20, v29, v19 op_sel:[0,1,0] op_sel_hi:[0,1,0]
	s_waitcnt lgkmcnt(4)
	ds_read_b64 v[84:85], v6 offset:7184
	ds_read_b128 v[86:89], v6 offset:7440
	ds_read_b128 v[90:93], v6 offset:7696
	ds_read_u16 v94, v7 offset:7184
	v_fma_mix_f32 v14, v10, v38, 0 op_sel:[0,0,0] op_sel_hi:[0,1,0]
	v_fma_mix_f32 v52, v10, v32, 0 op_sel:[0,0,0] op_sel_hi:[0,1,0]
	v_fma_mix_f32 v14, v11, v38, v14 op_sel:[0,1,0] op_sel_hi:[0,1,0]
	v_fma_mix_f32 v52, v11, v32, v52 op_sel:[0,1,0] op_sel_hi:[0,1,0]
	v_fma_mix_f32 v14, v12, v39, v14 op_sel:[0,0,0] op_sel_hi:[0,1,0]
	v_fma_mix_f32 v52, v12, v33, v52 op_sel:[0,0,0] op_sel_hi:[0,1,0]
	v_fma_mix_f32 v14, v13, v39, v14 op_sel:[0,1,0] op_sel_hi:[0,1,0]
	v_fma_mix_f32 v16, v10, v36, 0 op_sel:[0,0,0] op_sel_hi:[0,1,0]
	v_fma_mix_f32 v17, v11, v36, 0 op_sel:[0,1,0] op_sel_hi:[0,1,0]
	v_add_f32_dpp v20, v14, v14 quad_perm:[1,0,3,2] row_mask:0xf bank_mask:0xf bound_ctrl:1
	v_fma_mix_f32 v52, v13, v33, v52 op_sel:[0,1,0] op_sel_hi:[0,1,0]
	v_fma_mix_f32 v18, v12, v37, 0 op_sel:[0,0,0] op_sel_hi:[0,1,0]
	v_add_f32_dpp v20, v20, v20 quad_perm:[2,3,0,1] row_mask:0xf bank_mask:0xf bound_ctrl:1
	v_fma_mix_f32 v19, v13, v37, 0 op_sel:[0,1,0] op_sel_hi:[0,1,0]
	v_fma_mix_f32 v16, v46, v42, v16 op_sel:[0,0,0] op_sel_hi:[1,1,0]
	v_add_f32_dpp v20, v20, v20 row_half_mirror row_mask:0xf bank_mask:0xf bound_ctrl:1
	v_fma_mix_f32 v17, v46, v42, v17 op_sel:[0,1,0] op_sel_hi:[1,1,0]
	v_fma_mix_f32 v18, v46, v43, v18 op_sel:[0,0,0] op_sel_hi:[1,1,0]
	v_add_f32_dpp v20, v20, v20 row_mirror row_mask:0xf bank_mask:0xf bound_ctrl:1
	v_fma_mix_f32 v19, v46, v43, v19 op_sel:[0,1,0] op_sel_hi:[1,1,0]
	v_fma_mix_f32 v10, v20, v40, v16 op_sel:[0,0,0] op_sel_hi:[0,1,0]
	v_fma_mix_f32 v11, v20, v40, v17 op_sel:[0,1,0] op_sel_hi:[0,1,0]
	v_fma_mix_f32 v12, v20, v41, v18 op_sel:[0,0,0] op_sel_hi:[0,1,0]
	v_fma_mix_f32 v13, v20, v41, v19 op_sel:[0,1,0] op_sel_hi:[0,1,0]
	s_waitcnt lgkmcnt(4)
	ds_read_b64 v[24:25], v6 offset:8208
	ds_read_b128 v[26:29], v6 offset:8464
	ds_read_b128 v[30:33], v6 offset:8720
	ds_read_u16 v34, v7 offset:8208
	v_fma_mix_f32 v14, v10, v74, 0 op_sel:[0,0,0] op_sel_hi:[0,1,0]
	v_fma_mix_f32 v53, v10, v44, 0 op_sel:[0,0,0] op_sel_hi:[0,1,0]
	v_fma_mix_f32 v14, v11, v74, v14 op_sel:[0,1,0] op_sel_hi:[0,1,0]
	v_fma_mix_f32 v53, v11, v44, v53 op_sel:[0,1,0] op_sel_hi:[0,1,0]
	v_fma_mix_f32 v14, v12, v75, v14 op_sel:[0,0,0] op_sel_hi:[0,1,0]
	v_fma_mix_f32 v53, v12, v45, v53 op_sel:[0,0,0] op_sel_hi:[0,1,0]
	v_fma_mix_f32 v14, v13, v75, v14 op_sel:[0,1,0] op_sel_hi:[0,1,0]
	v_fma_mix_f32 v16, v10, v72, 0 op_sel:[0,0,0] op_sel_hi:[0,1,0]
	v_fma_mix_f32 v17, v11, v72, 0 op_sel:[0,1,0] op_sel_hi:[0,1,0]
	v_add_f32_dpp v20, v14, v14 quad_perm:[1,0,3,2] row_mask:0xf bank_mask:0xf bound_ctrl:1
	v_fma_mix_f32 v53, v13, v45, v53 op_sel:[0,1,0] op_sel_hi:[0,1,0]
	v_fma_mix_f32 v18, v12, v73, 0 op_sel:[0,0,0] op_sel_hi:[0,1,0]
	v_add_f32_dpp v20, v20, v20 quad_perm:[2,3,0,1] row_mask:0xf bank_mask:0xf bound_ctrl:1
	v_fma_mix_f32 v19, v13, v73, 0 op_sel:[0,1,0] op_sel_hi:[0,1,0]
	v_fma_mix_f32 v16, v82, v78, v16 op_sel:[0,0,0] op_sel_hi:[1,1,0]
	v_add_f32_dpp v20, v20, v20 row_half_mirror row_mask:0xf bank_mask:0xf bound_ctrl:1
	v_fma_mix_f32 v17, v82, v78, v17 op_sel:[0,1,0] op_sel_hi:[1,1,0]
	v_fma_mix_f32 v18, v82, v79, v18 op_sel:[0,0,0] op_sel_hi:[1,1,0]
	v_add_f32_dpp v20, v20, v20 row_mirror row_mask:0xf bank_mask:0xf bound_ctrl:1
	v_fma_mix_f32 v19, v82, v79, v19 op_sel:[0,1,0] op_sel_hi:[1,1,0]
	v_fma_mix_f32 v10, v20, v76, v16 op_sel:[0,0,0] op_sel_hi:[0,1,0]
	v_fma_mix_f32 v11, v20, v76, v17 op_sel:[0,1,0] op_sel_hi:[0,1,0]
	v_fma_mix_f32 v12, v20, v77, v18 op_sel:[0,0,0] op_sel_hi:[0,1,0]
	v_fma_mix_f32 v13, v20, v77, v19 op_sel:[0,1,0] op_sel_hi:[0,1,0]
	s_waitcnt lgkmcnt(4)
	ds_read_b64 v[36:37], v6 offset:9232
	ds_read_b128 v[38:41], v6 offset:9488
	ds_read_b128 v[42:45], v6 offset:9744
	ds_read_u16 v46, v7 offset:9232
	v_fma_mix_f32 v14, v10, v86, 0 op_sel:[0,0,0] op_sel_hi:[0,1,0]
	v_fma_mix_f32 v54, v10, v80, 0 op_sel:[0,0,0] op_sel_hi:[0,1,0]
	v_fma_mix_f32 v14, v11, v86, v14 op_sel:[0,1,0] op_sel_hi:[0,1,0]
	v_fma_mix_f32 v54, v11, v80, v54 op_sel:[0,1,0] op_sel_hi:[0,1,0]
	v_fma_mix_f32 v14, v12, v87, v14 op_sel:[0,0,0] op_sel_hi:[0,1,0]
	v_fma_mix_f32 v54, v12, v81, v54 op_sel:[0,0,0] op_sel_hi:[0,1,0]
	v_fma_mix_f32 v14, v13, v87, v14 op_sel:[0,1,0] op_sel_hi:[0,1,0]
	v_fma_mix_f32 v16, v10, v84, 0 op_sel:[0,0,0] op_sel_hi:[0,1,0]
	v_fma_mix_f32 v17, v11, v84, 0 op_sel:[0,1,0] op_sel_hi:[0,1,0]
	v_add_f32_dpp v20, v14, v14 quad_perm:[1,0,3,2] row_mask:0xf bank_mask:0xf bound_ctrl:1
	v_fma_mix_f32 v54, v13, v81, v54 op_sel:[0,1,0] op_sel_hi:[0,1,0]
	v_fma_mix_f32 v18, v12, v85, 0 op_sel:[0,0,0] op_sel_hi:[0,1,0]
	v_add_f32_dpp v20, v20, v20 quad_perm:[2,3,0,1] row_mask:0xf bank_mask:0xf bound_ctrl:1
	v_fma_mix_f32 v19, v13, v85, 0 op_sel:[0,1,0] op_sel_hi:[0,1,0]
	v_fma_mix_f32 v16, v94, v90, v16 op_sel:[0,0,0] op_sel_hi:[1,1,0]
	v_add_f32_dpp v20, v20, v20 row_half_mirror row_mask:0xf bank_mask:0xf bound_ctrl:1
	v_fma_mix_f32 v17, v94, v90, v17 op_sel:[0,1,0] op_sel_hi:[1,1,0]
	v_fma_mix_f32 v18, v94, v91, v18 op_sel:[0,0,0] op_sel_hi:[1,1,0]
	v_add_f32_dpp v20, v20, v20 row_mirror row_mask:0xf bank_mask:0xf bound_ctrl:1
	v_fma_mix_f32 v19, v94, v91, v19 op_sel:[0,1,0] op_sel_hi:[1,1,0]
	v_fma_mix_f32 v10, v20, v88, v16 op_sel:[0,0,0] op_sel_hi:[0,1,0]
	v_fma_mix_f32 v11, v20, v88, v17 op_sel:[0,1,0] op_sel_hi:[0,1,0]
	v_fma_mix_f32 v12, v20, v89, v18 op_sel:[0,0,0] op_sel_hi:[0,1,0]
	v_fma_mix_f32 v13, v20, v89, v19 op_sel:[0,1,0] op_sel_hi:[0,1,0]
	s_waitcnt lgkmcnt(4)
	ds_read_b64 v[72:73], v6 offset:10256
	ds_read_b128 v[74:77], v6 offset:10512
	ds_read_b128 v[78:81], v6 offset:10768
	ds_read_u16 v82, v7 offset:10256
	v_fma_mix_f32 v14, v10, v26, 0 op_sel:[0,0,0] op_sel_hi:[0,1,0]
	v_fma_mix_f32 v55, v10, v92, 0 op_sel:[0,0,0] op_sel_hi:[0,1,0]
	v_fma_mix_f32 v14, v11, v26, v14 op_sel:[0,1,0] op_sel_hi:[0,1,0]
	v_fma_mix_f32 v55, v11, v92, v55 op_sel:[0,1,0] op_sel_hi:[0,1,0]
	v_fma_mix_f32 v14, v12, v27, v14 op_sel:[0,0,0] op_sel_hi:[0,1,0]
	v_fma_mix_f32 v55, v12, v93, v55 op_sel:[0,0,0] op_sel_hi:[0,1,0]
	v_fma_mix_f32 v14, v13, v27, v14 op_sel:[0,1,0] op_sel_hi:[0,1,0]
	v_fma_mix_f32 v16, v10, v24, 0 op_sel:[0,0,0] op_sel_hi:[0,1,0]
	v_fma_mix_f32 v17, v11, v24, 0 op_sel:[0,1,0] op_sel_hi:[0,1,0]
	v_add_f32_dpp v20, v14, v14 quad_perm:[1,0,3,2] row_mask:0xf bank_mask:0xf bound_ctrl:1
	v_fma_mix_f32 v55, v13, v93, v55 op_sel:[0,1,0] op_sel_hi:[0,1,0]
	v_fma_mix_f32 v18, v12, v25, 0 op_sel:[0,0,0] op_sel_hi:[0,1,0]
	v_add_f32_dpp v20, v20, v20 quad_perm:[2,3,0,1] row_mask:0xf bank_mask:0xf bound_ctrl:1
	v_fma_mix_f32 v19, v13, v25, 0 op_sel:[0,1,0] op_sel_hi:[0,1,0]
	v_fma_mix_f32 v16, v34, v30, v16 op_sel:[0,0,0] op_sel_hi:[1,1,0]
	v_add_f32_dpp v20, v20, v20 row_half_mirror row_mask:0xf bank_mask:0xf bound_ctrl:1
	v_fma_mix_f32 v17, v34, v30, v17 op_sel:[0,1,0] op_sel_hi:[1,1,0]
	v_fma_mix_f32 v18, v34, v31, v18 op_sel:[0,0,0] op_sel_hi:[1,1,0]
	v_add_f32_dpp v20, v20, v20 row_mirror row_mask:0xf bank_mask:0xf bound_ctrl:1
	v_fma_mix_f32 v19, v34, v31, v19 op_sel:[0,1,0] op_sel_hi:[1,1,0]
	v_fma_mix_f32 v10, v20, v28, v16 op_sel:[0,0,0] op_sel_hi:[0,1,0]
	v_fma_mix_f32 v11, v20, v28, v17 op_sel:[0,1,0] op_sel_hi:[0,1,0]
	v_fma_mix_f32 v12, v20, v29, v18 op_sel:[0,0,0] op_sel_hi:[0,1,0]
	v_fma_mix_f32 v13, v20, v29, v19 op_sel:[0,1,0] op_sel_hi:[0,1,0]
	s_waitcnt lgkmcnt(4)
	ds_read_b64 v[84:85], v6 offset:11280
	ds_read_b128 v[86:89], v6 offset:11536
	ds_read_b128 v[90:93], v6 offset:11792
	ds_read_u16 v94, v7 offset:11280
	v_fma_mix_f32 v14, v10, v38, 0 op_sel:[0,0,0] op_sel_hi:[0,1,0]
	v_fma_mix_f32 v56, v10, v32, 0 op_sel:[0,0,0] op_sel_hi:[0,1,0]
	v_fma_mix_f32 v14, v11, v38, v14 op_sel:[0,1,0] op_sel_hi:[0,1,0]
	v_fma_mix_f32 v56, v11, v32, v56 op_sel:[0,1,0] op_sel_hi:[0,1,0]
	v_fma_mix_f32 v14, v12, v39, v14 op_sel:[0,0,0] op_sel_hi:[0,1,0]
	v_fma_mix_f32 v56, v12, v33, v56 op_sel:[0,0,0] op_sel_hi:[0,1,0]
	v_fma_mix_f32 v14, v13, v39, v14 op_sel:[0,1,0] op_sel_hi:[0,1,0]
	v_fma_mix_f32 v16, v10, v36, 0 op_sel:[0,0,0] op_sel_hi:[0,1,0]
	v_fma_mix_f32 v17, v11, v36, 0 op_sel:[0,1,0] op_sel_hi:[0,1,0]
	v_add_f32_dpp v20, v14, v14 quad_perm:[1,0,3,2] row_mask:0xf bank_mask:0xf bound_ctrl:1
	v_fma_mix_f32 v56, v13, v33, v56 op_sel:[0,1,0] op_sel_hi:[0,1,0]
	v_fma_mix_f32 v18, v12, v37, 0 op_sel:[0,0,0] op_sel_hi:[0,1,0]
	v_add_f32_dpp v20, v20, v20 quad_perm:[2,3,0,1] row_mask:0xf bank_mask:0xf bound_ctrl:1
	v_fma_mix_f32 v19, v13, v37, 0 op_sel:[0,1,0] op_sel_hi:[0,1,0]
	v_fma_mix_f32 v16, v46, v42, v16 op_sel:[0,0,0] op_sel_hi:[1,1,0]
	v_add_f32_dpp v20, v20, v20 row_half_mirror row_mask:0xf bank_mask:0xf bound_ctrl:1
	v_fma_mix_f32 v17, v46, v42, v17 op_sel:[0,1,0] op_sel_hi:[1,1,0]
	v_fma_mix_f32 v18, v46, v43, v18 op_sel:[0,0,0] op_sel_hi:[1,1,0]
	v_add_f32_dpp v20, v20, v20 row_mirror row_mask:0xf bank_mask:0xf bound_ctrl:1
	v_fma_mix_f32 v19, v46, v43, v19 op_sel:[0,1,0] op_sel_hi:[1,1,0]
	v_fma_mix_f32 v10, v20, v40, v16 op_sel:[0,0,0] op_sel_hi:[0,1,0]
	v_fma_mix_f32 v11, v20, v40, v17 op_sel:[0,1,0] op_sel_hi:[0,1,0]
	v_fma_mix_f32 v12, v20, v41, v18 op_sel:[0,0,0] op_sel_hi:[0,1,0]
	v_fma_mix_f32 v13, v20, v41, v19 op_sel:[0,1,0] op_sel_hi:[0,1,0]
	s_waitcnt lgkmcnt(4)
	ds_read_b64 v[24:25], v6 offset:12304
	ds_read_b128 v[26:29], v6 offset:12560
	ds_read_b128 v[30:33], v6 offset:12816
	ds_read_u16 v34, v7 offset:12304
	v_fma_mix_f32 v14, v10, v74, 0 op_sel:[0,0,0] op_sel_hi:[0,1,0]
	v_fma_mix_f32 v57, v10, v44, 0 op_sel:[0,0,0] op_sel_hi:[0,1,0]
	v_fma_mix_f32 v14, v11, v74, v14 op_sel:[0,1,0] op_sel_hi:[0,1,0]
	v_fma_mix_f32 v57, v11, v44, v57 op_sel:[0,1,0] op_sel_hi:[0,1,0]
	v_fma_mix_f32 v14, v12, v75, v14 op_sel:[0,0,0] op_sel_hi:[0,1,0]
	v_fma_mix_f32 v57, v12, v45, v57 op_sel:[0,0,0] op_sel_hi:[0,1,0]
	v_fma_mix_f32 v14, v13, v75, v14 op_sel:[0,1,0] op_sel_hi:[0,1,0]
	v_fma_mix_f32 v16, v10, v72, 0 op_sel:[0,0,0] op_sel_hi:[0,1,0]
	v_fma_mix_f32 v17, v11, v72, 0 op_sel:[0,1,0] op_sel_hi:[0,1,0]
	v_add_f32_dpp v20, v14, v14 quad_perm:[1,0,3,2] row_mask:0xf bank_mask:0xf bound_ctrl:1
	v_fma_mix_f32 v57, v13, v45, v57 op_sel:[0,1,0] op_sel_hi:[0,1,0]
	v_fma_mix_f32 v18, v12, v73, 0 op_sel:[0,0,0] op_sel_hi:[0,1,0]
	v_add_f32_dpp v20, v20, v20 quad_perm:[2,3,0,1] row_mask:0xf bank_mask:0xf bound_ctrl:1
	v_fma_mix_f32 v19, v13, v73, 0 op_sel:[0,1,0] op_sel_hi:[0,1,0]
	v_fma_mix_f32 v16, v82, v78, v16 op_sel:[0,0,0] op_sel_hi:[1,1,0]
	v_add_f32_dpp v20, v20, v20 row_half_mirror row_mask:0xf bank_mask:0xf bound_ctrl:1
	v_fma_mix_f32 v17, v82, v78, v17 op_sel:[0,1,0] op_sel_hi:[1,1,0]
	v_fma_mix_f32 v18, v82, v79, v18 op_sel:[0,0,0] op_sel_hi:[1,1,0]
	v_add_f32_dpp v20, v20, v20 row_mirror row_mask:0xf bank_mask:0xf bound_ctrl:1
	v_fma_mix_f32 v19, v82, v79, v19 op_sel:[0,1,0] op_sel_hi:[1,1,0]
	v_fma_mix_f32 v10, v20, v76, v16 op_sel:[0,0,0] op_sel_hi:[0,1,0]
	v_fma_mix_f32 v11, v20, v76, v17 op_sel:[0,1,0] op_sel_hi:[0,1,0]
	v_fma_mix_f32 v12, v20, v77, v18 op_sel:[0,0,0] op_sel_hi:[0,1,0]
	v_fma_mix_f32 v13, v20, v77, v19 op_sel:[0,1,0] op_sel_hi:[0,1,0]
	s_waitcnt lgkmcnt(4)
	ds_read_b64 v[36:37], v6 offset:13328
	ds_read_b128 v[38:41], v6 offset:13584
	ds_read_b128 v[42:45], v6 offset:13840
	ds_read_u16 v46, v7 offset:13328
	v_fma_mix_f32 v14, v10, v86, 0 op_sel:[0,0,0] op_sel_hi:[0,1,0]
	v_fma_mix_f32 v58, v10, v80, 0 op_sel:[0,0,0] op_sel_hi:[0,1,0]
	v_fma_mix_f32 v14, v11, v86, v14 op_sel:[0,1,0] op_sel_hi:[0,1,0]
	v_fma_mix_f32 v58, v11, v80, v58 op_sel:[0,1,0] op_sel_hi:[0,1,0]
	v_fma_mix_f32 v14, v12, v87, v14 op_sel:[0,0,0] op_sel_hi:[0,1,0]
	v_fma_mix_f32 v58, v12, v81, v58 op_sel:[0,0,0] op_sel_hi:[0,1,0]
	v_fma_mix_f32 v14, v13, v87, v14 op_sel:[0,1,0] op_sel_hi:[0,1,0]
	v_fma_mix_f32 v16, v10, v84, 0 op_sel:[0,0,0] op_sel_hi:[0,1,0]
	v_fma_mix_f32 v17, v11, v84, 0 op_sel:[0,1,0] op_sel_hi:[0,1,0]
	v_add_f32_dpp v20, v14, v14 quad_perm:[1,0,3,2] row_mask:0xf bank_mask:0xf bound_ctrl:1
	v_fma_mix_f32 v58, v13, v81, v58 op_sel:[0,1,0] op_sel_hi:[0,1,0]
	v_fma_mix_f32 v18, v12, v85, 0 op_sel:[0,0,0] op_sel_hi:[0,1,0]
	v_add_f32_dpp v20, v20, v20 quad_perm:[2,3,0,1] row_mask:0xf bank_mask:0xf bound_ctrl:1
	v_fma_mix_f32 v19, v13, v85, 0 op_sel:[0,1,0] op_sel_hi:[0,1,0]
	v_fma_mix_f32 v16, v94, v90, v16 op_sel:[0,0,0] op_sel_hi:[1,1,0]
	v_add_f32_dpp v20, v20, v20 row_half_mirror row_mask:0xf bank_mask:0xf bound_ctrl:1
	v_fma_mix_f32 v17, v94, v90, v17 op_sel:[0,1,0] op_sel_hi:[1,1,0]
	v_fma_mix_f32 v18, v94, v91, v18 op_sel:[0,0,0] op_sel_hi:[1,1,0]
	v_add_f32_dpp v20, v20, v20 row_mirror row_mask:0xf bank_mask:0xf bound_ctrl:1
	v_fma_mix_f32 v19, v94, v91, v19 op_sel:[0,1,0] op_sel_hi:[1,1,0]
	v_fma_mix_f32 v10, v20, v88, v16 op_sel:[0,0,0] op_sel_hi:[0,1,0]
	v_fma_mix_f32 v11, v20, v88, v17 op_sel:[0,1,0] op_sel_hi:[0,1,0]
	v_fma_mix_f32 v12, v20, v89, v18 op_sel:[0,0,0] op_sel_hi:[0,1,0]
	v_fma_mix_f32 v13, v20, v89, v19 op_sel:[0,1,0] op_sel_hi:[0,1,0]
	s_waitcnt lgkmcnt(4)
	ds_read_b64 v[72:73], v6 offset:14352
	ds_read_b128 v[74:77], v6 offset:14608
	ds_read_b128 v[78:81], v6 offset:14864
	ds_read_u16 v82, v7 offset:14352
	v_fma_mix_f32 v14, v10, v26, 0 op_sel:[0,0,0] op_sel_hi:[0,1,0]
	v_fma_mix_f32 v59, v10, v92, 0 op_sel:[0,0,0] op_sel_hi:[0,1,0]
	v_fma_mix_f32 v14, v11, v26, v14 op_sel:[0,1,0] op_sel_hi:[0,1,0]
	v_fma_mix_f32 v59, v11, v92, v59 op_sel:[0,1,0] op_sel_hi:[0,1,0]
	v_fma_mix_f32 v14, v12, v27, v14 op_sel:[0,0,0] op_sel_hi:[0,1,0]
	v_fma_mix_f32 v59, v12, v93, v59 op_sel:[0,0,0] op_sel_hi:[0,1,0]
	v_fma_mix_f32 v14, v13, v27, v14 op_sel:[0,1,0] op_sel_hi:[0,1,0]
	v_fma_mix_f32 v16, v10, v24, 0 op_sel:[0,0,0] op_sel_hi:[0,1,0]
	v_fma_mix_f32 v17, v11, v24, 0 op_sel:[0,1,0] op_sel_hi:[0,1,0]
	v_add_f32_dpp v20, v14, v14 quad_perm:[1,0,3,2] row_mask:0xf bank_mask:0xf bound_ctrl:1
	v_fma_mix_f32 v59, v13, v93, v59 op_sel:[0,1,0] op_sel_hi:[0,1,0]
	v_fma_mix_f32 v18, v12, v25, 0 op_sel:[0,0,0] op_sel_hi:[0,1,0]
	v_add_f32_dpp v20, v20, v20 quad_perm:[2,3,0,1] row_mask:0xf bank_mask:0xf bound_ctrl:1
	v_fma_mix_f32 v19, v13, v25, 0 op_sel:[0,1,0] op_sel_hi:[0,1,0]
	v_fma_mix_f32 v16, v34, v30, v16 op_sel:[0,0,0] op_sel_hi:[1,1,0]
	v_add_f32_dpp v20, v20, v20 row_half_mirror row_mask:0xf bank_mask:0xf bound_ctrl:1
	v_fma_mix_f32 v17, v34, v30, v17 op_sel:[0,1,0] op_sel_hi:[1,1,0]
	v_fma_mix_f32 v18, v34, v31, v18 op_sel:[0,0,0] op_sel_hi:[1,1,0]
	v_add_f32_dpp v20, v20, v20 row_mirror row_mask:0xf bank_mask:0xf bound_ctrl:1
	v_fma_mix_f32 v19, v34, v31, v19 op_sel:[0,1,0] op_sel_hi:[1,1,0]
	v_fma_mix_f32 v10, v20, v28, v16 op_sel:[0,0,0] op_sel_hi:[0,1,0]
	v_fma_mix_f32 v11, v20, v28, v17 op_sel:[0,1,0] op_sel_hi:[0,1,0]
	v_fma_mix_f32 v12, v20, v29, v18 op_sel:[0,0,0] op_sel_hi:[0,1,0]
	v_fma_mix_f32 v13, v20, v29, v19 op_sel:[0,1,0] op_sel_hi:[0,1,0]
	s_waitcnt lgkmcnt(4)
; DEVINL u16 f2bf(float a) { return (u16)(pk2(a, 0.f) & 0xffffu); }
; #define RW_STEP2(B) RW_STEP(B, WvA, XA, KrA, vhA, WvB, XB, KrB, vhB); RW_STEP((B) + 1, WvB, XB, KrB, vhB, WvA, XA, KrA, vhA)
; #define RW_STEP4(B) RW_STEP2(B); RW_STEP2((B) + 2)
; template <int DIR>
; DEVINL void rwkv_scan_dir(const Params& p, int task, int lane, int wave) {
;     ...
; #pragma unroll 1
;   for (int st = 0; st < 4096; st += 32) {
;     RW_STEP(0, WvA, XA, KrA, vhA, WvB, XB, KrB, vhB);
;     if (st > 0) { const int q0 = st - 16 + seg; yo[(long)(DIR ? (4095 - q0) : q0) * 1024] = f2bf(ykeep); }
;     RW_STEP(1, WvB, XB, KrB, vhB, WvA, XA, KrA, vhA);
;     RW_STEP2(2); RW_STEP4(4); RW_STEP4(8); RW_STEP4(12);
;     RW_STEP(16, WvA, XA, KrA, vhA, WvB, XB, KrB, vhB);
;     { const int q0 = st + seg; yo[(long)(DIR ? (4095 - q0) : q0) * 1024] = f2bf(ykeep); }
;     RW_STEP(17, WvB, XB, KrB, vhB, WvA, XA, KrA, vhA);
;     RW_STEP2(18); RW_STEP4(20); RW_STEP4(24); RW_STEP4(28);
;   }
	ds_read_b128 v[100:103], v9
	ds_read_b64 v[84:85], v6 offset:15376
	ds_read_b128 v[86:89], v6 offset:15632
	ds_read_b128 v[90:93], v6 offset:15888
	ds_read_u16 v94, v7 offset:15376
	v_fma_mix_f32 v14, v10, v38, 0 op_sel:[0,0,0] op_sel_hi:[0,1,0]
	v_fma_mix_f32 v60, v10, v32, 0 op_sel:[0,0,0] op_sel_hi:[0,1,0]
	v_fma_mix_f32 v14, v11, v38, v14 op_sel:[0,1,0] op_sel_hi:[0,1,0]
	v_fma_mix_f32 v60, v11, v32, v60 op_sel:[0,1,0] op_sel_hi:[0,1,0]
	v_fma_mix_f32 v14, v12, v39, v14 op_sel:[0,0,0] op_sel_hi:[0,1,0]
	v_fma_mix_f32 v60, v12, v33, v60 op_sel:[0,0,0] op_sel_hi:[0,1,0]
	v_fma_mix_f32 v14, v13, v39, v14 op_sel:[0,1,0] op_sel_hi:[0,1,0]
	v_fma_mix_f32 v16, v10, v36, 0 op_sel:[0,0,0] op_sel_hi:[0,1,0]
	v_fma_mix_f32 v17, v11, v36, 0 op_sel:[0,1,0] op_sel_hi:[0,1,0]
	v_add_f32_dpp v20, v14, v14 quad_perm:[1,0,3,2] row_mask:0xf bank_mask:0xf bound_ctrl:1
	v_fma_mix_f32 v60, v13, v33, v60 op_sel:[0,1,0] op_sel_hi:[0,1,0]
	v_fma_mix_f32 v18, v12, v37, 0 op_sel:[0,0,0] op_sel_hi:[0,1,0]
	v_add_f32_dpp v20, v20, v20 quad_perm:[2,3,0,1] row_mask:0xf bank_mask:0xf bound_ctrl:1
	v_fma_mix_f32 v19, v13, v37, 0 op_sel:[0,1,0] op_sel_hi:[0,1,0]
	v_fma_mix_f32 v16, v46, v42, v16 op_sel:[0,0,0] op_sel_hi:[1,1,0]
	v_add_f32_dpp v20, v20, v20 row_half_mirror row_mask:0xf bank_mask:0xf bound_ctrl:1
	v_fma_mix_f32 v17, v46, v42, v17 op_sel:[0,1,0] op_sel_hi:[1,1,0]
	v_fma_mix_f32 v18, v46, v43, v18 op_sel:[0,0,0] op_sel_hi:[1,1,0]
	v_add_f32_dpp v20, v20, v20 row_mirror row_mask:0xf bank_mask:0xf bound_ctrl:1
	v_fma_mix_f32 v19, v46, v43, v19 op_sel:[0,1,0] op_sel_hi:[1,1,0]
	v_fma_mix_f32 v10, v20, v40, v16 op_sel:[0,0,0] op_sel_hi:[0,1,0]
	v_fma_mix_f32 v11, v20, v40, v17 op_sel:[0,1,0] op_sel_hi:[0,1,0]
	v_fma_mix_f32 v12, v20, v41, v18 op_sel:[0,0,0] op_sel_hi:[0,1,0]
	v_fma_mix_f32 v13, v20, v41, v19 op_sel:[0,1,0] op_sel_hi:[0,1,0]
	s_waitcnt lgkmcnt(4)
	v_add_u32_e32 v6, 0x4000, v6
	v_add_u32_e32 v7, 0x4000, v7
	v_and_b32_e32 v6, 0x1ffff, v6
	v_and_b32_e32 v7, 0x1ffff, v7
	ds_read_b64 v[24:25], v6 offset:16
	ds_read_b128 v[26:29], v6 offset:272
	ds_read_b128 v[30:33], v6 offset:528
	ds_read_u16 v34, v7 offset:16
	v_fma_mix_f32 v14, v10, v74, 0 op_sel:[0,0,0] op_sel_hi:[0,1,0]
	v_fma_mix_f32 v61, v10, v44, 0 op_sel:[0,0,0] op_sel_hi:[0,1,0]
	v_fma_mix_f32 v14, v11, v74, v14 op_sel:[0,1,0] op_sel_hi:[0,1,0]
	v_fma_mix_f32 v61, v11, v44, v61 op_sel:[0,1,0] op_sel_hi:[0,1,0]
	v_fma_mix_f32 v14, v12, v75, v14 op_sel:[0,0,0] op_sel_hi:[0,1,0]
	v_fma_mix_f32 v61, v12, v45, v61 op_sel:[0,0,0] op_sel_hi:[0,1,0]
	v_fma_mix_f32 v14, v13, v75, v14 op_sel:[0,1,0] op_sel_hi:[0,1,0]
	v_fma_mix_f32 v16, v10, v72, 0 op_sel:[0,0,0] op_sel_hi:[0,1,0]
	v_fma_mix_f32 v17, v11, v72, 0 op_sel:[0,1,0] op_sel_hi:[0,1,0]
	v_add_f32_dpp v20, v14, v14 quad_perm:[1,0,3,2] row_mask:0xf bank_mask:0xf bound_ctrl:1
	v_fma_mix_f32 v61, v13, v45, v61 op_sel:[0,1,0] op_sel_hi:[0,1,0]
	v_fma_mix_f32 v18, v12, v73, 0 op_sel:[0,0,0] op_sel_hi:[0,1,0]
	v_add_f32_dpp v20, v20, v20 quad_perm:[2,3,0,1] row_mask:0xf bank_mask:0xf bound_ctrl:1
	v_fma_mix_f32 v19, v13, v73, 0 op_sel:[0,1,0] op_sel_hi:[0,1,0]
	v_fma_mix_f32 v16, v82, v78, v16 op_sel:[0,0,0] op_sel_hi:[1,1,0]
	v_add_f32_dpp v20, v20, v20 row_half_mirror row_mask:0xf bank_mask:0xf bound_ctrl:1
	v_fma_mix_f32 v17, v82, v78, v17 op_sel:[0,1,0] op_sel_hi:[1,1,0]
	v_fma_mix_f32 v18, v82, v79, v18 op_sel:[0,0,0] op_sel_hi:[1,1,0]
	v_add_f32_dpp v20, v20, v20 row_mirror row_mask:0xf bank_mask:0xf bound_ctrl:1
	v_fma_mix_f32 v19, v82, v79, v19 op_sel:[0,1,0] op_sel_hi:[1,1,0]
	v_fma_mix_f32 v10, v20, v76, v16 op_sel:[0,0,0] op_sel_hi:[0,1,0]
	v_fma_mix_f32 v11, v20, v76, v17 op_sel:[0,1,0] op_sel_hi:[0,1,0]
	v_fma_mix_f32 v12, v20, v77, v18 op_sel:[0,0,0] op_sel_hi:[0,1,0]
	v_fma_mix_f32 v13, v20, v77, v19 op_sel:[0,1,0] op_sel_hi:[0,1,0]
	s_waitcnt lgkmcnt(4)
	ds_read_b64 v[36:37], v6 offset:1040
	ds_read_b128 v[38:41], v6 offset:1296
	ds_read_b128 v[42:45], v6 offset:1552
	ds_read_u16 v46, v7 offset:1040
	v_fma_mix_f32 v14, v10, v86, 0 op_sel:[0,0,0] op_sel_hi:[0,1,0]
	v_fma_mix_f32 v62, v10, v80, 0 op_sel:[0,0,0] op_sel_hi:[0,1,0]
	v_fma_mix_f32 v14, v11, v86, v14 op_sel:[0,1,0] op_sel_hi:[0,1,0]
	v_fma_mix_f32 v62, v11, v80, v62 op_sel:[0,1,0] op_sel_hi:[0,1,0]
	v_fma_mix_f32 v14, v12, v87, v14 op_sel:[0,0,0] op_sel_hi:[0,1,0]
	v_fma_mix_f32 v62, v12, v81, v62 op_sel:[0,0,0] op_sel_hi:[0,1,0]
	v_fma_mix_f32 v14, v13, v87, v14 op_sel:[0,1,0] op_sel_hi:[0,1,0]
	v_fma_mix_f32 v16, v10, v84, 0 op_sel:[0,0,0] op_sel_hi:[0,1,0]
	v_fma_mix_f32 v17, v11, v84, 0 op_sel:[0,1,0] op_sel_hi:[0,1,0]
	v_add_f32_dpp v20, v14, v14 quad_perm:[1,0,3,2] row_mask:0xf bank_mask:0xf bound_ctrl:1
	v_fma_mix_f32 v62, v13, v81, v62 op_sel:[0,1,0] op_sel_hi:[0,1,0]
	v_fma_mix_f32 v18, v12, v85, 0 op_sel:[0,0,0] op_sel_hi:[0,1,0]
	v_add_f32_dpp v20, v20, v20 quad_perm:[2,3,0,1] row_mask:0xf bank_mask:0xf bound_ctrl:1
	v_fma_mix_f32 v19, v13, v85, 0 op_sel:[0,1,0] op_sel_hi:[0,1,0]
	v_fma_mix_f32 v16, v94, v90, v16 op_sel:[0,0,0] op_sel_hi:[1,1,0]
	v_add_f32_dpp v20, v20, v20 row_half_mirror row_mask:0xf bank_mask:0xf bound_ctrl:1
	v_fma_mix_f32 v17, v94, v90, v17 op_sel:[0,1,0] op_sel_hi:[1,1,0]
	v_fma_mix_f32 v18, v94, v91, v18 op_sel:[0,0,0] op_sel_hi:[1,1,0]
	v_add_f32_dpp v20, v20, v20 row_mirror row_mask:0xf bank_mask:0xf bound_ctrl:1
	v_fma_mix_f32 v19, v94, v91, v19 op_sel:[0,1,0] op_sel_hi:[1,1,0]
	v_fma_mix_f32 v10, v20, v88, v16 op_sel:[0,0,0] op_sel_hi:[0,1,0]
	v_fma_mix_f32 v11, v20, v88, v17 op_sel:[0,1,0] op_sel_hi:[0,1,0]
	v_fma_mix_f32 v12, v20, v89, v18 op_sel:[0,0,0] op_sel_hi:[0,1,0]
	v_fma_mix_f32 v13, v20, v89, v19 op_sel:[0,1,0] op_sel_hi:[0,1,0]
	s_waitcnt lgkmcnt(4)
	s_add_u32 s15, s15, 1
	s_add_u32 s14, s14, 1
	s_cmp_lt_u32 s14, 0x100
	s_cbranch_scc1 .Lrw_blk_d0
; DEVINL u16 f2bf(float a) { return (u16)(pk2(a, 0.f) & 0xffffu); }
; #define RW_LANDED(WN, XN, KN, VN) asm volatile("s_waitcnt lgkmcnt(0)" : "+v"(WN), "+v"(XN), "+v"(KN), "+v"(VN) :: "memory")
; #define RW_DMA4(B) RW_DMA_ONLY(B); RW_DMA_ONLY((B) + 1); RW_DMA_ONLY((B) + 2); RW_DMA_ONLY((B) + 3)
; template <int DIR>
; DEVINL void rwkv_scan_dir(const Params& p, int task, int lane, int wave) {
;     ...
;   const char* recbase = p.ws + O_REC + ((long)(b * 16 + head) * 4096) * 1024 + lane * 16;
;   const unsigned ring_lds = (unsigned)(unsigned long)(__attribute__((address_space(3))) char*)(dynsmem + wave * 32768);
;   const unsigned ring_u = __builtin_amdgcn_readfirstlane(ring_lds);
;   const unsigned a_seg = ring_lds + seg * 64;
;   const unsigned a_v = ring_lds + (row >> 2) * 64 + 48 + (row & 3) * 2;
;   u16* yo = (u16*)(p.ws + (DIR ? O_YB : O_YSUM)) + ((long)b * 4096) * 1024 + head * 64 + row;
;   float s0 = 0.f, s1 = 0.f, s2 = 0.f, s3 = 0.f;
;   float ykeep = 0.f;
;   const char* recdir = recbase + (DIR ? (long)4095 * 1024 : 0);
;     ...
;   u32x2 WvA, WvB; u32x4 XA, XB, KrA, KrB; unsigned vhA, vhB;
;   RW_DMA4(0); RW_DMA4(4); RW_DMA4(8); RW_DMA4(12); RW_DMA4(16); RW_DMA4(20);
;   RW_READ(0, WvA, XA, KrA, vhA, 23);
;   RW_LANDED(WvA, XA, KrA, vhA);
;   float ypart = 0.f;
;     ...
;   {
;     const float ylast = allred16(ypart);
;     ykeep = (seg == 15) ? ylast : ykeep;
;     const int q0 = 4096 - 16 + seg; yo[(long)(DIR ? (4095 - q0) : q0) * 1024] = f2bf(ykeep);
;   }
	v_fma_mix_f32 v21, v10, v92, 0 op_sel:[0,0,0] op_sel_hi:[0,1,0]
	v_fma_mix_f32 v22, v12, v93, 0 op_sel:[0,0,0] op_sel_hi:[0,1,0]
	v_fma_mix_f32 v21, v11, v92, v21 op_sel:[0,1,0] op_sel_hi:[0,1,0]
	v_fma_mix_f32 v22, v13, v93, v22 op_sel:[0,1,0] op_sel_hi:[0,1,0]
	v_add_f32_e32 v63, v21, v22
	s_nop 1
	v_add_f32_dpp v48, v48, v48 row_ror:8 row_mask:0xf bank_mask:0x3
	v_add_f32_dpp v49, v49, v49 row_ror:8 row_mask:0xf bank_mask:0x3
	v_add_f32_dpp v50, v50, v50 row_ror:8 row_mask:0xf bank_mask:0x3
	v_add_f32_dpp v51, v51, v51 row_ror:8 row_mask:0xf bank_mask:0x3
	v_add_f32_dpp v52, v52, v52 row_ror:8 row_mask:0xf bank_mask:0x3
	v_add_f32_dpp v53, v53, v53 row_ror:8 row_mask:0xf bank_mask:0x3
	v_add_f32_dpp v54, v54, v54 row_ror:8 row_mask:0xf bank_mask:0x3
	v_add_f32_dpp v55, v55, v55 row_ror:8 row_mask:0xf bank_mask:0x3
	v_add_f32_dpp v48, v56, v56 row_ror:8 row_mask:0xf bank_mask:0xc
	v_add_f32_dpp v49, v57, v57 row_ror:8 row_mask:0xf bank_mask:0xc
	v_add_f32_dpp v50, v58, v58 row_ror:8 row_mask:0xf bank_mask:0xc
	v_add_f32_dpp v51, v59, v59 row_ror:8 row_mask:0xf bank_mask:0xc
	v_add_f32_dpp v52, v60, v60 row_ror:8 row_mask:0xf bank_mask:0xc
	v_add_f32_dpp v53, v61, v61 row_ror:8 row_mask:0xf bank_mask:0xc
	v_add_f32_dpp v54, v62, v62 row_ror:8 row_mask:0xf bank_mask:0xc
	v_add_f32_dpp v55, v63, v63 row_ror:8 row_mask:0xf bank_mask:0xc
	v_add_f32_dpp v48, v48, v48 row_ror:12 row_mask:0xf bank_mask:0x5
	v_add_f32_dpp v49, v49, v49 row_ror:12 row_mask:0xf bank_mask:0x5
	v_add_f32_dpp v50, v50, v50 row_ror:12 row_mask:0xf bank_mask:0x5
	v_add_f32_dpp v51, v51, v51 row_ror:12 row_mask:0xf bank_mask:0x5
	v_add_f32_dpp v48, v52, v52 row_ror:4 row_mask:0xf bank_mask:0xa
	v_add_f32_dpp v49, v53, v53 row_ror:4 row_mask:0xf bank_mask:0xa
	v_add_f32_dpp v50, v54, v54 row_ror:4 row_mask:0xf bank_mask:0xa
	v_add_f32_dpp v51, v55, v55 row_ror:4 row_mask:0xf bank_mask:0xa
	v_add_f32_dpp v64, v48, v48 quad_perm:[2,3,0,1] row_mask:0xf bank_mask:0xf bound_ctrl:1
	v_add_f32_dpp v65, v50, v50 quad_perm:[2,3,0,1] row_mask:0xf bank_mask:0xf bound_ctrl:1
	v_cndmask_b32_e64 v56, v64, v65, s[50:51]
	v_add_f32_dpp v64, v49, v49 quad_perm:[2,3,0,1] row_mask:0xf bank_mask:0xf bound_ctrl:1
	v_add_f32_dpp v65, v51, v51 quad_perm:[2,3,0,1] row_mask:0xf bank_mask:0xf bound_ctrl:1
	v_cndmask_b32_e64 v57, v64, v65, s[50:51]
	v_add_f32_dpp v64, v56, v56 quad_perm:[1,0,3,2] row_mask:0xf bank_mask:0xf bound_ctrl:1
	s_nop 0
	v_add_f32_dpp v65, v57, v57 quad_perm:[1,0,3,2] row_mask:0xf bank_mask:0xf bound_ctrl:1
	v_cndmask_b32_e64 v66, v64, v65, s[48:49]
	v_cvt_pk_bf16_f32 v66, v66, v66
	global_store_short v8, v66, s[12:13]
	s_add_u32 s12, s12, 0x8000
	s_addc_u32 s13, s13, 0
	s_branch .Lrw_next
.Lrw_bwd:
	s_add_u32 s12, s12, 0x1f700000
	s_addc_u32 s13, s13, 0
	v_sub_u32_e32 v69, 0xfff, v3
	v_lshl_add_u32 v8, v69, 11, v8
	s_add_u32 s10, s10, 0x3ff000
	s_addc_u32 s11, s11, 0
	s_sub_u32 s10, s10, s39
	s_subb_u32 s11, s11, 0
	s_sub_u32 s40, 0x1f000, s39
	s_mov_b32 s41, 0
	v_lshlrev_b32_e32 v6, 4, v3
	v_add_u32_e32 v6, 0x1c000, v6
	s_add_u32 s3, s37, 0x1c300
	v_lshl_add_u32 v7, v4, 1, s3
	s_add_u32 s3, s40, s41
	s_and_b32 s3, s3, 0x1ffff
	s_add_u32 s3, s3, 16
	s_mov_b32 m0, s3
	s_nop 0
	global_load_lds_dwordx4 v5, s[10:11] offset:0
	global_load_lds_dwordx4 v5, s[10:11] offset:1024
	global_load_lds_dwordx4 v5, s[10:11] offset:2048
	global_load_lds_dwordx4 v5, s[10:11] offset:3072
	s_sub_u32 s10, s10, 0x4000
	s_subb_u32 s11, s11, 0
	s_sub_u32 s41, s41, 0x4000
	s_and_b32 s41, s41, 0x1ffff
	s_add_u32 s3, s40, s41
	s_and_b32 s3, s3, 0x1ffff
	s_add_u32 s3, s3, 16
	s_mov_b32 m0, s3
	s_nop 0
	global_load_lds_dwordx4 v5, s[10:11] offset:0
	global_load_lds_dwordx4 v5, s[10:11] offset:1024
	global_load_lds_dwordx4 v5, s[10:11] offset:2048
	global_load_lds_dwordx4 v5, s[10:11] offset:3072
	s_sub_u32 s10, s10, 0x4000
	s_subb_u32 s11, s11, 0
	s_sub_u32 s41, s41, 0x4000
	s_and_b32 s41, s41, 0x1ffff
	s_add_u32 s3, s40, s41
	s_and_b32 s3, s3, 0x1ffff
	s_add_u32 s3, s3, 16
	s_mov_b32 m0, s3
	s_nop 0
	global_load_lds_dwordx4 v5, s[10:11] offset:0
	global_load_lds_dwordx4 v5, s[10:11] offset:1024
	global_load_lds_dwordx4 v5, s[10:11] offset:2048
	global_load_lds_dwordx4 v5, s[10:11] offset:3072
	s_sub_u32 s10, s10, 0x4000
	s_subb_u32 s11, s11, 0
	s_sub_u32 s41, s41, 0x4000
	s_and_b32 s41, s41, 0x1ffff
	s_waitcnt vmcnt(0)
	v_mov_b32_e32 v10, 0
	v_mov_b32_e32 v11, 0
	v_mov_b32_e32 v12, 0
	v_mov_b32_e32 v13, 0
	s_mov_b32 s14, 0
	s_add_u32 s3, s15, 3
	v_mov_b32_e32 v69, s3
	ds_write_b32 v23, v69
	s_add_u32 s43, s15, 2
	s_mov_b32 s42, 0

.Lrw_skip_d1:
	ds_read_b64 v[84:85], v6 offset:12312
	ds_read_b128 v[86:89], v6 offset:12560
	ds_read_b128 v[90:93], v6 offset:12816
	ds_read_u16 v94, v7 offset:12304
	v_fma_mix_f32 v14, v10, v38, 0 op_sel:[0,0,0] op_sel_hi:[0,1,0]
	v_fma_mix_f32 v48, v10, v32, 0 op_sel:[0,0,0] op_sel_hi:[0,1,0]
	v_fma_mix_f32 v14, v11, v38, v14 op_sel:[0,1,0] op_sel_hi:[0,1,0]
	v_fma_mix_f32 v48, v11, v32, v48 op_sel:[0,1,0] op_sel_hi:[0,1,0]
	v_fma_mix_f32 v14, v12, v39, v14 op_sel:[0,0,0] op_sel_hi:[0,1,0]
	v_fma_mix_f32 v48, v12, v33, v48 op_sel:[0,0,0] op_sel_hi:[0,1,0]
	v_fma_mix_f32 v14, v13, v39, v14 op_sel:[0,1,0] op_sel_hi:[0,1,0]
	v_fma_mix_f32 v16, v10, v36, 0 op_sel:[0,0,0] op_sel_hi:[0,1,0]
	v_fma_mix_f32 v17, v11, v36, 0 op_sel:[0,1,0] op_sel_hi:[0,1,0]
	v_add_f32_dpp v20, v14, v14 quad_perm:[1,0,3,2] row_mask:0xf bank_mask:0xf bound_ctrl:1
	v_fma_mix_f32 v48, v13, v33, v48 op_sel:[0,1,0] op_sel_hi:[0,1,0]
	v_fma_mix_f32 v18, v12, v37, 0 op_sel:[0,0,0] op_sel_hi:[0,1,0]
	v_add_f32_dpp v20, v20, v20 quad_perm:[2,3,0,1] row_mask:0xf bank_mask:0xf bound_ctrl:1
	v_fma_mix_f32 v19, v13, v37, 0 op_sel:[0,1,0] op_sel_hi:[0,1,0]
	v_fma_mix_f32 v16, v46, v42, v16 op_sel:[0,0,0] op_sel_hi:[1,1,0]
	v_add_f32_dpp v20, v20, v20 row_half_mirror row_mask:0xf bank_mask:0xf bound_ctrl:1
	v_fma_mix_f32 v17, v46, v42, v17 op_sel:[0,1,0] op_sel_hi:[1,1,0]
	v_fma_mix_f32 v18, v46, v43, v18 op_sel:[0,0,0] op_sel_hi:[1,1,0]
	v_add_f32_dpp v20, v20, v20 row_mirror row_mask:0xf bank_mask:0xf bound_ctrl:1
	v_fma_mix_f32 v19, v46, v43, v19 op_sel:[0,1,0] op_sel_hi:[1,1,0]
	v_fma_mix_f32 v10, v20, v40, v16 op_sel:[0,0,0] op_sel_hi:[0,1,0]
	v_fma_mix_f32 v11, v20, v40, v17 op_sel:[0,1,0] op_sel_hi:[0,1,0]
	v_fma_mix_f32 v12, v20, v41, v18 op_sel:[0,0,0] op_sel_hi:[0,1,0]
	v_fma_mix_f32 v13, v20, v41, v19 op_sel:[0,1,0] op_sel_hi:[0,1,0]
	s_waitcnt lgkmcnt(4)
	ds_read_b64 v[24:25], v6 offset:11288
	ds_read_b128 v[26:29], v6 offset:11536
	ds_read_b128 v[30:33], v6 offset:11792
	ds_read_u16 v34, v7 offset:11280
	v_fma_mix_f32 v14, v10, v74, 0 op_sel:[0,0,0] op_sel_hi:[0,1,0]
	v_fma_mix_f32 v49, v10, v44, 0 op_sel:[0,0,0] op_sel_hi:[0,1,0]
	v_fma_mix_f32 v14, v11, v74, v14 op_sel:[0,1,0] op_sel_hi:[0,1,0]
	v_fma_mix_f32 v49, v11, v44, v49 op_sel:[0,1,0] op_sel_hi:[0,1,0]
	v_fma_mix_f32 v14, v12, v75, v14 op_sel:[0,0,0] op_sel_hi:[0,1,0]
	v_fma_mix_f32 v49, v12, v45, v49 op_sel:[0,0,0] op_sel_hi:[0,1,0]
	v_fma_mix_f32 v14, v13, v75, v14 op_sel:[0,1,0] op_sel_hi:[0,1,0]
	v_fma_mix_f32 v16, v10, v72, 0 op_sel:[0,0,0] op_sel_hi:[0,1,0]
	v_fma_mix_f32 v17, v11, v72, 0 op_sel:[0,1,0] op_sel_hi:[0,1,0]
	v_add_f32_dpp v20, v14, v14 quad_perm:[1,0,3,2] row_mask:0xf bank_mask:0xf bound_ctrl:1
	v_fma_mix_f32 v49, v13, v45, v49 op_sel:[0,1,0] op_sel_hi:[0,1,0]
	v_fma_mix_f32 v18, v12, v73, 0 op_sel:[0,0,0] op_sel_hi:[0,1,0]
	v_add_f32_dpp v20, v20, v20 quad_perm:[2,3,0,1] row_mask:0xf bank_mask:0xf bound_ctrl:1
	v_fma_mix_f32 v19, v13, v73, 0 op_sel:[0,1,0] op_sel_hi:[0,1,0]
	v_fma_mix_f32 v16, v82, v78, v16 op_sel:[0,0,0] op_sel_hi:[1,1,0]
	v_add_f32_dpp v20, v20, v20 row_half_mirror row_mask:0xf bank_mask:0xf bound_ctrl:1
	v_fma_mix_f32 v17, v82, v78, v17 op_sel:[0,1,0] op_sel_hi:[1,1,0]
	v_fma_mix_f32 v18, v82, v79, v18 op_sel:[0,0,0] op_sel_hi:[1,1,0]
	v_add_f32_dpp v20, v20, v20 row_mirror row_mask:0xf bank_mask:0xf bound_ctrl:1
	v_fma_mix_f32 v19, v82, v79, v19 op_sel:[0,1,0] op_sel_hi:[1,1,0]
	v_fma_mix_f32 v10, v20, v76, v16 op_sel:[0,0,0] op_sel_hi:[0,1,0]
	v_fma_mix_f32 v11, v20, v76, v17 op_sel:[0,1,0] op_sel_hi:[0,1,0]
	v_fma_mix_f32 v12, v20, v77, v18 op_sel:[0,0,0] op_sel_hi:[0,1,0]
	v_fma_mix_f32 v13, v20, v77, v19 op_sel:[0,1,0] op_sel_hi:[0,1,0]
	s_waitcnt lgkmcnt(4)
	ds_read_b64 v[36:37], v6 offset:10264
	ds_read_b128 v[38:41], v6 offset:10512
	ds_read_b128 v[42:45], v6 offset:10768
	ds_read_u16 v46, v7 offset:10256
	v_fma_mix_f32 v14, v10, v86, 0 op_sel:[0,0,0] op_sel_hi:[0,1,0]
	v_fma_mix_f32 v50, v10, v80, 0 op_sel:[0,0,0] op_sel_hi:[0,1,0]
	v_fma_mix_f32 v14, v11, v86, v14 op_sel:[0,1,0] op_sel_hi:[0,1,0]
	v_fma_mix_f32 v50, v11, v80, v50 op_sel:[0,1,0] op_sel_hi:[0,1,0]
	v_fma_mix_f32 v14, v12, v87, v14 op_sel:[0,0,0] op_sel_hi:[0,1,0]
	v_fma_mix_f32 v50, v12, v81, v50 op_sel:[0,0,0] op_sel_hi:[0,1,0]
	v_fma_mix_f32 v14, v13, v87, v14 op_sel:[0,1,0] op_sel_hi:[0,1,0]
	v_fma_mix_f32 v16, v10, v84, 0 op_sel:[0,0,0] op_sel_hi:[0,1,0]
	v_fma_mix_f32 v17, v11, v84, 0 op_sel:[0,1,0] op_sel_hi:[0,1,0]
	v_add_f32_dpp v20, v14, v14 quad_perm:[1,0,3,2] row_mask:0xf bank_mask:0xf bound_ctrl:1
	v_fma_mix_f32 v50, v13, v81, v50 op_sel:[0,1,0] op_sel_hi:[0,1,0]
	v_fma_mix_f32 v18, v12, v85, 0 op_sel:[0,0,0] op_sel_hi:[0,1,0]
	v_add_f32_dpp v20, v20, v20 quad_perm:[2,3,0,1] row_mask:0xf bank_mask:0xf bound_ctrl:1
	v_fma_mix_f32 v19, v13, v85, 0 op_sel:[0,1,0] op_sel_hi:[0,1,0]
	v_fma_mix_f32 v16, v94, v90, v16 op_sel:[0,0,0] op_sel_hi:[1,1,0]
	v_add_f32_dpp v20, v20, v20 row_half_mirror row_mask:0xf bank_mask:0xf bound_ctrl:1
	v_fma_mix_f32 v17, v94, v90, v17 op_sel:[0,1,0] op_sel_hi:[1,1,0]
	v_fma_mix_f32 v18, v94, v91, v18 op_sel:[0,0,0] op_sel_hi:[1,1,0]
	v_add_f32_dpp v20, v20, v20 row_mirror row_mask:0xf bank_mask:0xf bound_ctrl:1
	v_fma_mix_f32 v19, v94, v91, v19 op_sel:[0,1,0] op_sel_hi:[1,1,0]
	v_fma_mix_f32 v10, v20, v88, v16 op_sel:[0,0,0] op_sel_hi:[0,1,0]
	v_fma_mix_f32 v11, v20, v88, v17 op_sel:[0,1,0] op_sel_hi:[0,1,0]
	v_fma_mix_f32 v12, v20, v89, v18 op_sel:[0,0,0] op_sel_hi:[0,1,0]
	v_fma_mix_f32 v13, v20, v89, v19 op_sel:[0,1,0] op_sel_hi:[0,1,0]
	s_waitcnt lgkmcnt(4)
	ds_read_b64 v[72:73], v6 offset:9240
	ds_read_b128 v[74:77], v6 offset:9488
	ds_read_b128 v[78:81], v6 offset:9744
	ds_read_u16 v82, v7 offset:9232
	v_fma_mix_f32 v14, v10, v26, 0 op_sel:[0,0,0] op_sel_hi:[0,1,0]
	v_fma_mix_f32 v51, v10, v92, 0 op_sel:[0,0,0] op_sel_hi:[0,1,0]
	v_fma_mix_f32 v14, v11, v26, v14 op_sel:[0,1,0] op_sel_hi:[0,1,0]
	v_fma_mix_f32 v51, v11, v92, v51 op_sel:[0,1,0] op_sel_hi:[0,1,0]
	v_fma_mix_f32 v14, v12, v27, v14 op_sel:[0,0,0] op_sel_hi:[0,1,0]
	v_fma_mix_f32 v51, v12, v93, v51 op_sel:[0,0,0] op_sel_hi:[0,1,0]
	v_fma_mix_f32 v14, v13, v27, v14 op_sel:[0,1,0] op_sel_hi:[0,1,0]
	v_fma_mix_f32 v16, v10, v24, 0 op_sel:[0,0,0] op_sel_hi:[0,1,0]
	v_fma_mix_f32 v17, v11, v24, 0 op_sel:[0,1,0] op_sel_hi:[0,1,0]
	v_add_f32_dpp v20, v14, v14 quad_perm:[1,0,3,2] row_mask:0xf bank_mask:0xf bound_ctrl:1
	v_fma_mix_f32 v51, v13, v93, v51 op_sel:[0,1,0] op_sel_hi:[0,1,0]
	v_fma_mix_f32 v18, v12, v25, 0 op_sel:[0,0,0] op_sel_hi:[0,1,0]
	v_add_f32_dpp v20, v20, v20 quad_perm:[2,3,0,1] row_mask:0xf bank_mask:0xf bound_ctrl:1
	v_fma_mix_f32 v19, v13, v25, 0 op_sel:[0,1,0] op_sel_hi:[0,1,0]
	v_fma_mix_f32 v16, v34, v30, v16 op_sel:[0,0,0] op_sel_hi:[1,1,0]
	v_add_f32_dpp v20, v20, v20 row_half_mirror row_mask:0xf bank_mask:0xf bound_ctrl:1
	v_fma_mix_f32 v17, v34, v30, v17 op_sel:[0,1,0] op_sel_hi:[1,1,0]
	v_fma_mix_f32 v18, v34, v31, v18 op_sel:[0,0,0] op_sel_hi:[1,1,0]
	v_add_f32_dpp v20, v20, v20 row_mirror row_mask:0xf bank_mask:0xf bound_ctrl:1
	v_fma_mix_f32 v19, v34, v31, v19 op_sel:[0,1,0] op_sel_hi:[1,1,0]
	v_fma_mix_f32 v10, v20, v28, v16 op_sel:[0,0,0] op_sel_hi:[0,1,0]
	v_fma_mix_f32 v11, v20, v28, v17 op_sel:[0,1,0] op_sel_hi:[0,1,0]
	v_fma_mix_f32 v12, v20, v29, v18 op_sel:[0,0,0] op_sel_hi:[0,1,0]
	v_fma_mix_f32 v13, v20, v29, v19 op_sel:[0,1,0] op_sel_hi:[0,1,0]
	s_waitcnt lgkmcnt(4)
	ds_read_b64 v[84:85], v6 offset:8216
	ds_read_b128 v[86:89], v6 offset:8464
	ds_read_b128 v[90:93], v6 offset:8720
	ds_read_u16 v94, v7 offset:8208
	v_fma_mix_f32 v14, v10, v38, 0 op_sel:[0,0,0] op_sel_hi:[0,1,0]
	v_fma_mix_f32 v52, v10, v32, 0 op_sel:[0,0,0] op_sel_hi:[0,1,0]
	v_fma_mix_f32 v14, v11, v38, v14 op_sel:[0,1,0] op_sel_hi:[0,1,0]
	v_fma_mix_f32 v52, v11, v32, v52 op_sel:[0,1,0] op_sel_hi:[0,1,0]
	v_fma_mix_f32 v14, v12, v39, v14 op_sel:[0,0,0] op_sel_hi:[0,1,0]
	v_fma_mix_f32 v52, v12, v33, v52 op_sel:[0,0,0] op_sel_hi:[0,1,0]
	v_fma_mix_f32 v14, v13, v39, v14 op_sel:[0,1,0] op_sel_hi:[0,1,0]
	v_fma_mix_f32 v16, v10, v36, 0 op_sel:[0,0,0] op_sel_hi:[0,1,0]
	v_fma_mix_f32 v17, v11, v36, 0 op_sel:[0,1,0] op_sel_hi:[0,1,0]
	v_add_f32_dpp v20, v14, v14 quad_perm:[1,0,3,2] row_mask:0xf bank_mask:0xf bound_ctrl:1
	v_fma_mix_f32 v52, v13, v33, v52 op_sel:[0,1,0] op_sel_hi:[0,1,0]
	v_fma_mix_f32 v18, v12, v37, 0 op_sel:[0,0,0] op_sel_hi:[0,1,0]
	v_add_f32_dpp v20, v20, v20 quad_perm:[2,3,0,1] row_mask:0xf bank_mask:0xf bound_ctrl:1
	v_fma_mix_f32 v19, v13, v37, 0 op_sel:[0,1,0] op_sel_hi:[0,1,0]
	v_fma_mix_f32 v16, v46, v42, v16 op_sel:[0,0,0] op_sel_hi:[1,1,0]
	v_add_f32_dpp v20, v20, v20 row_half_mirror row_mask:0xf bank_mask:0xf bound_ctrl:1
	v_fma_mix_f32 v17, v46, v42, v17 op_sel:[0,1,0] op_sel_hi:[1,1,0]
	v_fma_mix_f32 v18, v46, v43, v18 op_sel:[0,0,0] op_sel_hi:[1,1,0]
	v_add_f32_dpp v20, v20, v20 row_mirror row_mask:0xf bank_mask:0xf bound_ctrl:1
	v_fma_mix_f32 v19, v46, v43, v19 op_sel:[0,1,0] op_sel_hi:[1,1,0]
	v_fma_mix_f32 v10, v20, v40, v16 op_sel:[0,0,0] op_sel_hi:[0,1,0]
	v_fma_mix_f32 v11, v20, v40, v17 op_sel:[0,1,0] op_sel_hi:[0,1,0]
	v_fma_mix_f32 v12, v20, v41, v18 op_sel:[0,0,0] op_sel_hi:[0,1,0]
	v_fma_mix_f32 v13, v20, v41, v19 op_sel:[0,1,0] op_sel_hi:[0,1,0]
	s_waitcnt lgkmcnt(4)
	ds_read_b64 v[24:25], v6 offset:7192
	ds_read_b128 v[26:29], v6 offset:7440
	ds_read_b128 v[30:33], v6 offset:7696
	ds_read_u16 v34, v7 offset:7184
	v_fma_mix_f32 v14, v10, v74, 0 op_sel:[0,0,0] op_sel_hi:[0,1,0]
	v_fma_mix_f32 v53, v10, v44, 0 op_sel:[0,0,0] op_sel_hi:[0,1,0]
	v_fma_mix_f32 v14, v11, v74, v14 op_sel:[0,1,0] op_sel_hi:[0,1,0]
	v_fma_mix_f32 v53, v11, v44, v53 op_sel:[0,1,0] op_sel_hi:[0,1,0]
	v_fma_mix_f32 v14, v12, v75, v14 op_sel:[0,0,0] op_sel_hi:[0,1,0]
	v_fma_mix_f32 v53, v12, v45, v53 op_sel:[0,0,0] op_sel_hi:[0,1,0]
	v_fma_mix_f32 v14, v13, v75, v14 op_sel:[0,1,0] op_sel_hi:[0,1,0]
	v_fma_mix_f32 v16, v10, v72, 0 op_sel:[0,0,0] op_sel_hi:[0,1,0]
	v_fma_mix_f32 v17, v11, v72, 0 op_sel:[0,1,0] op_sel_hi:[0,1,0]
	v_add_f32_dpp v20, v14, v14 quad_perm:[1,0,3,2] row_mask:0xf bank_mask:0xf bound_ctrl:1
	v_fma_mix_f32 v53, v13, v45, v53 op_sel:[0,1,0] op_sel_hi:[0,1,0]
	v_fma_mix_f32 v18, v12, v73, 0 op_sel:[0,0,0] op_sel_hi:[0,1,0]
	v_add_f32_dpp v20, v20, v20 quad_perm:[2,3,0,1] row_mask:0xf bank_mask:0xf bound_ctrl:1
	v_fma_mix_f32 v19, v13, v73, 0 op_sel:[0,1,0] op_sel_hi:[0,1,0]
	v_fma_mix_f32 v16, v82, v78, v16 op_sel:[0,0,0] op_sel_hi:[1,1,0]
	v_add_f32_dpp v20, v20, v20 row_half_mirror row_mask:0xf bank_mask:0xf bound_ctrl:1
	v_fma_mix_f32 v17, v82, v78, v17 op_sel:[0,1,0] op_sel_hi:[1,1,0]
	v_fma_mix_f32 v18, v82, v79, v18 op_sel:[0,0,0] op_sel_hi:[1,1,0]
	v_add_f32_dpp v20, v20, v20 row_mirror row_mask:0xf bank_mask:0xf bound_ctrl:1
	v_fma_mix_f32 v19, v82, v79, v19 op_sel:[0,1,0] op_sel_hi:[1,1,0]
	v_fma_mix_f32 v10, v20, v76, v16 op_sel:[0,0,0] op_sel_hi:[0,1,0]
	v_fma_mix_f32 v11, v20, v76, v17 op_sel:[0,1,0] op_sel_hi:[0,1,0]
	v_fma_mix_f32 v12, v20, v77, v18 op_sel:[0,0,0] op_sel_hi:[0,1,0]
	v_fma_mix_f32 v13, v20, v77, v19 op_sel:[0,1,0] op_sel_hi:[0,1,0]
	s_waitcnt lgkmcnt(4)
	ds_read_b64 v[36:37], v6 offset:6168
	ds_read_b128 v[38:41], v6 offset:6416
	ds_read_b128 v[42:45], v6 offset:6672
	ds_read_u16 v46, v7 offset:6160
	v_fma_mix_f32 v14, v10, v86, 0 op_sel:[0,0,0] op_sel_hi:[0,1,0]
	v_fma_mix_f32 v54, v10, v80, 0 op_sel:[0,0,0] op_sel_hi:[0,1,0]
	v_fma_mix_f32 v14, v11, v86, v14 op_sel:[0,1,0] op_sel_hi:[0,1,0]
	v_fma_mix_f32 v54, v11, v80, v54 op_sel:[0,1,0] op_sel_hi:[0,1,0]
	v_fma_mix_f32 v14, v12, v87, v14 op_sel:[0,0,0] op_sel_hi:[0,1,0]
	v_fma_mix_f32 v54, v12, v81, v54 op_sel:[0,0,0] op_sel_hi:[0,1,0]
	v_fma_mix_f32 v14, v13, v87, v14 op_sel:[0,1,0] op_sel_hi:[0,1,0]
	v_fma_mix_f32 v16, v10, v84, 0 op_sel:[0,0,0] op_sel_hi:[0,1,0]
	v_fma_mix_f32 v17, v11, v84, 0 op_sel:[0,1,0] op_sel_hi:[0,1,0]
	v_add_f32_dpp v20, v14, v14 quad_perm:[1,0,3,2] row_mask:0xf bank_mask:0xf bound_ctrl:1
	v_fma_mix_f32 v54, v13, v81, v54 op_sel:[0,1,0] op_sel_hi:[0,1,0]
	v_fma_mix_f32 v18, v12, v85, 0 op_sel:[0,0,0] op_sel_hi:[0,1,0]
	v_add_f32_dpp v20, v20, v20 quad_perm:[2,3,0,1] row_mask:0xf bank_mask:0xf bound_ctrl:1
	v_fma_mix_f32 v19, v13, v85, 0 op_sel:[0,1,0] op_sel_hi:[0,1,0]
	v_fma_mix_f32 v16, v94, v90, v16 op_sel:[0,0,0] op_sel_hi:[1,1,0]
	v_add_f32_dpp v20, v20, v20 row_half_mirror row_mask:0xf bank_mask:0xf bound_ctrl:1
	v_fma_mix_f32 v17, v94, v90, v17 op_sel:[0,1,0] op_sel_hi:[1,1,0]
	v_fma_mix_f32 v18, v94, v91, v18 op_sel:[0,0,0] op_sel_hi:[1,1,0]
	v_add_f32_dpp v20, v20, v20 row_mirror row_mask:0xf bank_mask:0xf bound_ctrl:1
	v_fma_mix_f32 v19, v94, v91, v19 op_sel:[0,1,0] op_sel_hi:[1,1,0]
	v_fma_mix_f32 v10, v20, v88, v16 op_sel:[0,0,0] op_sel_hi:[0,1,0]
	v_fma_mix_f32 v11, v20, v88, v17 op_sel:[0,1,0] op_sel_hi:[0,1,0]
	v_fma_mix_f32 v12, v20, v89, v18 op_sel:[0,0,0] op_sel_hi:[0,1,0]
	v_fma_mix_f32 v13, v20, v89, v19 op_sel:[0,1,0] op_sel_hi:[0,1,0]
	s_waitcnt lgkmcnt(4)
	ds_read_b64 v[72:73], v6 offset:5144
	ds_read_b128 v[74:77], v6 offset:5392
	ds_read_b128 v[78:81], v6 offset:5648
	ds_read_u16 v82, v7 offset:5136
	v_fma_mix_f32 v14, v10, v26, 0 op_sel:[0,0,0] op_sel_hi:[0,1,0]
	v_fma_mix_f32 v55, v10, v92, 0 op_sel:[0,0,0] op_sel_hi:[0,1,0]
	v_fma_mix_f32 v14, v11, v26, v14 op_sel:[0,1,0] op_sel_hi:[0,1,0]
	v_fma_mix_f32 v55, v11, v92, v55 op_sel:[0,1,0] op_sel_hi:[0,1,0]
	v_fma_mix_f32 v14, v12, v27, v14 op_sel:[0,0,0] op_sel_hi:[0,1,0]
	v_fma_mix_f32 v55, v12, v93, v55 op_sel:[0,0,0] op_sel_hi:[0,1,0]
	v_fma_mix_f32 v14, v13, v27, v14 op_sel:[0,1,0] op_sel_hi:[0,1,0]
	v_fma_mix_f32 v16, v10, v24, 0 op_sel:[0,0,0] op_sel_hi:[0,1,0]
	v_fma_mix_f32 v17, v11, v24, 0 op_sel:[0,1,0] op_sel_hi:[0,1,0]
	v_add_f32_dpp v20, v14, v14 quad_perm:[1,0,3,2] row_mask:0xf bank_mask:0xf bound_ctrl:1
	v_fma_mix_f32 v55, v13, v93, v55 op_sel:[0,1,0] op_sel_hi:[0,1,0]
	v_fma_mix_f32 v18, v12, v25, 0 op_sel:[0,0,0] op_sel_hi:[0,1,0]
	v_add_f32_dpp v20, v20, v20 quad_perm:[2,3,0,1] row_mask:0xf bank_mask:0xf bound_ctrl:1
	v_fma_mix_f32 v19, v13, v25, 0 op_sel:[0,1,0] op_sel_hi:[0,1,0]
	v_fma_mix_f32 v16, v34, v30, v16 op_sel:[0,0,0] op_sel_hi:[1,1,0]
	v_add_f32_dpp v20, v20, v20 row_half_mirror row_mask:0xf bank_mask:0xf bound_ctrl:1
	v_fma_mix_f32 v17, v34, v30, v17 op_sel:[0,1,0] op_sel_hi:[1,1,0]
	v_fma_mix_f32 v18, v34, v31, v18 op_sel:[0,0,0] op_sel_hi:[1,1,0]
	v_add_f32_dpp v20, v20, v20 row_mirror row_mask:0xf bank_mask:0xf bound_ctrl:1
	v_fma_mix_f32 v19, v34, v31, v19 op_sel:[0,1,0] op_sel_hi:[1,1,0]
	v_fma_mix_f32 v10, v20, v28, v16 op_sel:[0,0,0] op_sel_hi:[0,1,0]
	v_fma_mix_f32 v11, v20, v28, v17 op_sel:[0,1,0] op_sel_hi:[0,1,0]
	v_fma_mix_f32 v12, v20, v29, v18 op_sel:[0,0,0] op_sel_hi:[0,1,0]
	v_fma_mix_f32 v13, v20, v29, v19 op_sel:[0,1,0] op_sel_hi:[0,1,0]
	s_waitcnt lgkmcnt(4)
	ds_read_b64 v[84:85], v6 offset:4120
	ds_read_b128 v[86:89], v6 offset:4368
	ds_read_b128 v[90:93], v6 offset:4624
	ds_read_u16 v94, v7 offset:4112
	v_fma_mix_f32 v14, v10, v38, 0 op_sel:[0,0,0] op_sel_hi:[0,1,0]
	v_fma_mix_f32 v56, v10, v32, 0 op_sel:[0,0,0] op_sel_hi:[0,1,0]
	v_fma_mix_f32 v14, v11, v38, v14 op_sel:[0,1,0] op_sel_hi:[0,1,0]
	v_fma_mix_f32 v56, v11, v32, v56 op_sel:[0,1,0] op_sel_hi:[0,1,0]
	v_fma_mix_f32 v14, v12, v39, v14 op_sel:[0,0,0] op_sel_hi:[0,1,0]
	v_fma_mix_f32 v56, v12, v33, v56 op_sel:[0,0,0] op_sel_hi:[0,1,0]
	v_fma_mix_f32 v14, v13, v39, v14 op_sel:[0,1,0] op_sel_hi:[0,1,0]
	v_fma_mix_f32 v16, v10, v36, 0 op_sel:[0,0,0] op_sel_hi:[0,1,0]
	v_fma_mix_f32 v17, v11, v36, 0 op_sel:[0,1,0] op_sel_hi:[0,1,0]
	v_add_f32_dpp v20, v14, v14 quad_perm:[1,0,3,2] row_mask:0xf bank_mask:0xf bound_ctrl:1
	v_fma_mix_f32 v56, v13, v33, v56 op_sel:[0,1,0] op_sel_hi:[0,1,0]
	v_fma_mix_f32 v18, v12, v37, 0 op_sel:[0,0,0] op_sel_hi:[0,1,0]
	v_add_f32_dpp v20, v20, v20 quad_perm:[2,3,0,1] row_mask:0xf bank_mask:0xf bound_ctrl:1
	v_fma_mix_f32 v19, v13, v37, 0 op_sel:[0,1,0] op_sel_hi:[0,1,0]
	v_fma_mix_f32 v16, v46, v42, v16 op_sel:[0,0,0] op_sel_hi:[1,1,0]
	v_add_f32_dpp v20, v20, v20 row_half_mirror row_mask:0xf bank_mask:0xf bound_ctrl:1
	v_fma_mix_f32 v17, v46, v42, v17 op_sel:[0,1,0] op_sel_hi:[1,1,0]
	v_fma_mix_f32 v18, v46, v43, v18 op_sel:[0,0,0] op_sel_hi:[1,1,0]
	v_add_f32_dpp v20, v20, v20 row_mirror row_mask:0xf bank_mask:0xf bound_ctrl:1
	v_fma_mix_f32 v19, v46, v43, v19 op_sel:[0,1,0] op_sel_hi:[1,1,0]
	v_fma_mix_f32 v10, v20, v40, v16 op_sel:[0,0,0] op_sel_hi:[0,1,0]
	v_fma_mix_f32 v11, v20, v40, v17 op_sel:[0,1,0] op_sel_hi:[0,1,0]
	v_fma_mix_f32 v12, v20, v41, v18 op_sel:[0,0,0] op_sel_hi:[0,1,0]
	v_fma_mix_f32 v13, v20, v41, v19 op_sel:[0,1,0] op_sel_hi:[0,1,0]
	s_waitcnt lgkmcnt(4)
	ds_read_b64 v[24:25], v6 offset:3096
	ds_read_b128 v[26:29], v6 offset:3344
	ds_read_b128 v[30:33], v6 offset:3600
	ds_read_u16 v34, v7 offset:3088
	v_fma_mix_f32 v14, v10, v74, 0 op_sel:[0,0,0] op_sel_hi:[0,1,0]
	v_fma_mix_f32 v57, v10, v44, 0 op_sel:[0,0,0] op_sel_hi:[0,1,0]
	v_fma_mix_f32 v14, v11, v74, v14 op_sel:[0,1,0] op_sel_hi:[0,1,0]
	v_fma_mix_f32 v57, v11, v44, v57 op_sel:[0,1,0] op_sel_hi:[0,1,0]
	v_fma_mix_f32 v14, v12, v75, v14 op_sel:[0,0,0] op_sel_hi:[0,1,0]
	v_fma_mix_f32 v57, v12, v45, v57 op_sel:[0,0,0] op_sel_hi:[0,1,0]
	v_fma_mix_f32 v14, v13, v75, v14 op_sel:[0,1,0] op_sel_hi:[0,1,0]
	v_fma_mix_f32 v16, v10, v72, 0 op_sel:[0,0,0] op_sel_hi:[0,1,0]
	v_fma_mix_f32 v17, v11, v72, 0 op_sel:[0,1,0] op_sel_hi:[0,1,0]
	v_add_f32_dpp v20, v14, v14 quad_perm:[1,0,3,2] row_mask:0xf bank_mask:0xf bound_ctrl:1
	v_fma_mix_f32 v57, v13, v45, v57 op_sel:[0,1,0] op_sel_hi:[0,1,0]
	v_fma_mix_f32 v18, v12, v73, 0 op_sel:[0,0,0] op_sel_hi:[0,1,0]
	v_add_f32_dpp v20, v20, v20 quad_perm:[2,3,0,1] row_mask:0xf bank_mask:0xf bound_ctrl:1
	v_fma_mix_f32 v19, v13, v73, 0 op_sel:[0,1,0] op_sel_hi:[0,1,0]
	v_fma_mix_f32 v16, v82, v78, v16 op_sel:[0,0,0] op_sel_hi:[1,1,0]
	v_add_f32_dpp v20, v20, v20 row_half_mirror row_mask:0xf bank_mask:0xf bound_ctrl:1
	v_fma_mix_f32 v17, v82, v78, v17 op_sel:[0,1,0] op_sel_hi:[1,1,0]
	v_fma_mix_f32 v18, v82, v79, v18 op_sel:[0,0,0] op_sel_hi:[1,1,0]
	v_add_f32_dpp v20, v20, v20 row_mirror row_mask:0xf bank_mask:0xf bound_ctrl:1
	v_fma_mix_f32 v19, v82, v79, v19 op_sel:[0,1,0] op_sel_hi:[1,1,0]
	v_fma_mix_f32 v10, v20, v76, v16 op_sel:[0,0,0] op_sel_hi:[0,1,0]
	v_fma_mix_f32 v11, v20, v76, v17 op_sel:[0,1,0] op_sel_hi:[0,1,0]
	v_fma_mix_f32 v12, v20, v77, v18 op_sel:[0,0,0] op_sel_hi:[0,1,0]
	v_fma_mix_f32 v13, v20, v77, v19 op_sel:[0,1,0] op_sel_hi:[0,1,0]
	s_waitcnt lgkmcnt(4)
	ds_read_b64 v[36:37], v6 offset:2072
	ds_read_b128 v[38:41], v6 offset:2320
	ds_read_b128 v[42:45], v6 offset:2576
	ds_read_u16 v46, v7 offset:2064
	v_fma_mix_f32 v14, v10, v86, 0 op_sel:[0,0,0] op_sel_hi:[0,1,0]
	v_fma_mix_f32 v58, v10, v80, 0 op_sel:[0,0,0] op_sel_hi:[0,1,0]
	v_fma_mix_f32 v14, v11, v86, v14 op_sel:[0,1,0] op_sel_hi:[0,1,0]
	v_fma_mix_f32 v58, v11, v80, v58 op_sel:[0,1,0] op_sel_hi:[0,1,0]
	v_fma_mix_f32 v14, v12, v87, v14 op_sel:[0,0,0] op_sel_hi:[0,1,0]
	v_fma_mix_f32 v58, v12, v81, v58 op_sel:[0,0,0] op_sel_hi:[0,1,0]
	v_fma_mix_f32 v14, v13, v87, v14 op_sel:[0,1,0] op_sel_hi:[0,1,0]
	v_fma_mix_f32 v16, v10, v84, 0 op_sel:[0,0,0] op_sel_hi:[0,1,0]
	v_fma_mix_f32 v17, v11, v84, 0 op_sel:[0,1,0] op_sel_hi:[0,1,0]
	v_add_f32_dpp v20, v14, v14 quad_perm:[1,0,3,2] row_mask:0xf bank_mask:0xf bound_ctrl:1
	v_fma_mix_f32 v58, v13, v81, v58 op_sel:[0,1,0] op_sel_hi:[0,1,0]
	v_fma_mix_f32 v18, v12, v85, 0 op_sel:[0,0,0] op_sel_hi:[0,1,0]
	v_add_f32_dpp v20, v20, v20 quad_perm:[2,3,0,1] row_mask:0xf bank_mask:0xf bound_ctrl:1
	v_fma_mix_f32 v19, v13, v85, 0 op_sel:[0,1,0] op_sel_hi:[0,1,0]
	v_fma_mix_f32 v16, v94, v90, v16 op_sel:[0,0,0] op_sel_hi:[1,1,0]
	v_add_f32_dpp v20, v20, v20 row_half_mirror row_mask:0xf bank_mask:0xf bound_ctrl:1
	v_fma_mix_f32 v17, v94, v90, v17 op_sel:[0,1,0] op_sel_hi:[1,1,0]
	v_fma_mix_f32 v18, v94, v91, v18 op_sel:[0,0,0] op_sel_hi:[1,1,0]
	v_add_f32_dpp v20, v20, v20 row_mirror row_mask:0xf bank_mask:0xf bound_ctrl:1
	v_fma_mix_f32 v19, v94, v91, v19 op_sel:[0,1,0] op_sel_hi:[1,1,0]
	v_fma_mix_f32 v10, v20, v88, v16 op_sel:[0,0,0] op_sel_hi:[0,1,0]
	v_fma_mix_f32 v11, v20, v88, v17 op_sel:[0,1,0] op_sel_hi:[0,1,0]
	v_fma_mix_f32 v12, v20, v89, v18 op_sel:[0,0,0] op_sel_hi:[0,1,0]
	v_fma_mix_f32 v13, v20, v89, v19 op_sel:[0,1,0] op_sel_hi:[0,1,0]
	s_waitcnt lgkmcnt(4)
	ds_read_b64 v[72:73], v6 offset:1048
	ds_read_b128 v[74:77], v6 offset:1296
	ds_read_b128 v[78:81], v6 offset:1552
	ds_read_u16 v82, v7 offset:1040
	v_fma_mix_f32 v14, v10, v26, 0 op_sel:[0,0,0] op_sel_hi:[0,1,0]
	v_fma_mix_f32 v59, v10, v92, 0 op_sel:[0,0,0] op_sel_hi:[0,1,0]
	v_fma_mix_f32 v14, v11, v26, v14 op_sel:[0,1,0] op_sel_hi:[0,1,0]
	v_fma_mix_f32 v59, v11, v92, v59 op_sel:[0,1,0] op_sel_hi:[0,1,0]
	v_fma_mix_f32 v14, v12, v27, v14 op_sel:[0,0,0] op_sel_hi:[0,1,0]
	v_fma_mix_f32 v59, v12, v93, v59 op_sel:[0,0,0] op_sel_hi:[0,1,0]
	v_fma_mix_f32 v14, v13, v27, v14 op_sel:[0,1,0] op_sel_hi:[0,1,0]
	v_fma_mix_f32 v16, v10, v24, 0 op_sel:[0,0,0] op_sel_hi:[0,1,0]
	v_fma_mix_f32 v17, v11, v24, 0 op_sel:[0,1,0] op_sel_hi:[0,1,0]
	v_add_f32_dpp v20, v14, v14 quad_perm:[1,0,3,2] row_mask:0xf bank_mask:0xf bound_ctrl:1
	v_fma_mix_f32 v59, v13, v93, v59 op_sel:[0,1,0] op_sel_hi:[0,1,0]
	v_fma_mix_f32 v18, v12, v25, 0 op_sel:[0,0,0] op_sel_hi:[0,1,0]
	v_add_f32_dpp v20, v20, v20 quad_perm:[2,3,0,1] row_mask:0xf bank_mask:0xf bound_ctrl:1
	v_fma_mix_f32 v19, v13, v25, 0 op_sel:[0,1,0] op_sel_hi:[0,1,0]
	v_fma_mix_f32 v16, v34, v30, v16 op_sel:[0,0,0] op_sel_hi:[1,1,0]
	v_add_f32_dpp v20, v20, v20 row_half_mirror row_mask:0xf bank_mask:0xf bound_ctrl:1
	v_fma_mix_f32 v17, v34, v30, v17 op_sel:[0,1,0] op_sel_hi:[1,1,0]
	v_fma_mix_f32 v18, v34, v31, v18 op_sel:[0,0,0] op_sel_hi:[1,1,0]
	v_add_f32_dpp v20, v20, v20 row_mirror row_mask:0xf bank_mask:0xf bound_ctrl:1
	v_fma_mix_f32 v19, v34, v31, v19 op_sel:[0,1,0] op_sel_hi:[1,1,0]
	v_fma_mix_f32 v10, v20, v28, v16 op_sel:[0,0,0] op_sel_hi:[0,1,0]
	v_fma_mix_f32 v11, v20, v28, v17 op_sel:[0,1,0] op_sel_hi:[0,1,0]
	v_fma_mix_f32 v12, v20, v29, v18 op_sel:[0,0,0] op_sel_hi:[0,1,0]
	v_fma_mix_f32 v13, v20, v29, v19 op_sel:[0,1,0] op_sel_hi:[0,1,0]
	s_waitcnt lgkmcnt(4)
; DEVINL u16 f2bf(float a) { return (u16)(pk2(a, 0.f) & 0xffffu); }
; #define RW_STEP2(B) RW_STEP(B, WvA, XA, KrA, vhA, WvB, XB, KrB, vhB); RW_STEP((B) + 1, WvB, XB, KrB, vhB, WvA, XA, KrA, vhA)
; #define RW_STEP4(B) RW_STEP2(B); RW_STEP2((B) + 2)
; template <int DIR>
; DEVINL void rwkv_scan_dir(const Params& p, int task, int lane, int wave) {
;     ...
;   for (int st = 0; st < 4096; st += 32) {
;     RW_STEP(0, WvA, XA, KrA, vhA, WvB, XB, KrB, vhB);
;     if (st > 0) { const int q0 = st - 16 + seg; yo[(long)(DIR ? (4095 - q0) : q0) * 1024] = f2bf(ykeep); }
;     RW_STEP(1, WvB, XB, KrB, vhB, WvA, XA, KrA, vhA);
;     RW_STEP2(2); RW_STEP4(4); RW_STEP4(8); RW_STEP4(12);
;     RW_STEP(16, WvA, XA, KrA, vhA, WvB, XB, KrB, vhB);
;     { const int q0 = st + seg; yo[(long)(DIR ? (4095 - q0) : q0) * 1024] = f2bf(ykeep); }
;     RW_STEP(17, WvB, XB, KrB, vhB, WvA, XA, KrA, vhA);
;     RW_STEP2(18); RW_STEP4(20); RW_STEP4(24); RW_STEP4(28);
	ds_read_b128 v[100:103], v9
	ds_read_b64 v[84:85], v6 offset:24
	ds_read_b128 v[86:89], v6 offset:272
	ds_read_b128 v[90:93], v6 offset:528
	ds_read_u16 v94, v7 offset:16
	v_fma_mix_f32 v14, v10, v38, 0 op_sel:[0,0,0] op_sel_hi:[0,1,0]
	v_fma_mix_f32 v60, v10, v32, 0 op_sel:[0,0,0] op_sel_hi:[0,1,0]
	v_fma_mix_f32 v14, v11, v38, v14 op_sel:[0,1,0] op_sel_hi:[0,1,0]
	v_fma_mix_f32 v60, v11, v32, v60 op_sel:[0,1,0] op_sel_hi:[0,1,0]
	v_fma_mix_f32 v14, v12, v39, v14 op_sel:[0,0,0] op_sel_hi:[0,1,0]
	v_fma_mix_f32 v60, v12, v33, v60 op_sel:[0,0,0] op_sel_hi:[0,1,0]
	v_fma_mix_f32 v14, v13, v39, v14 op_sel:[0,1,0] op_sel_hi:[0,1,0]
	v_fma_mix_f32 v16, v10, v36, 0 op_sel:[0,0,0] op_sel_hi:[0,1,0]
	v_fma_mix_f32 v17, v11, v36, 0 op_sel:[0,1,0] op_sel_hi:[0,1,0]
	v_add_f32_dpp v20, v14, v14 quad_perm:[1,0,3,2] row_mask:0xf bank_mask:0xf bound_ctrl:1
	v_fma_mix_f32 v60, v13, v33, v60 op_sel:[0,1,0] op_sel_hi:[0,1,0]
	v_fma_mix_f32 v18, v12, v37, 0 op_sel:[0,0,0] op_sel_hi:[0,1,0]
	v_add_f32_dpp v20, v20, v20 quad_perm:[2,3,0,1] row_mask:0xf bank_mask:0xf bound_ctrl:1
	v_fma_mix_f32 v19, v13, v37, 0 op_sel:[0,1,0] op_sel_hi:[0,1,0]
	v_fma_mix_f32 v16, v46, v42, v16 op_sel:[0,0,0] op_sel_hi:[1,1,0]
	v_add_f32_dpp v20, v20, v20 row_half_mirror row_mask:0xf bank_mask:0xf bound_ctrl:1
	v_fma_mix_f32 v17, v46, v42, v17 op_sel:[0,1,0] op_sel_hi:[1,1,0]
	v_fma_mix_f32 v18, v46, v43, v18 op_sel:[0,0,0] op_sel_hi:[1,1,0]
	v_add_f32_dpp v20, v20, v20 row_mirror row_mask:0xf bank_mask:0xf bound_ctrl:1
	v_fma_mix_f32 v19, v46, v43, v19 op_sel:[0,1,0] op_sel_hi:[1,1,0]
	v_fma_mix_f32 v10, v20, v40, v16 op_sel:[0,0,0] op_sel_hi:[0,1,0]
	v_fma_mix_f32 v11, v20, v40, v17 op_sel:[0,1,0] op_sel_hi:[0,1,0]
	v_fma_mix_f32 v12, v20, v41, v18 op_sel:[0,0,0] op_sel_hi:[0,1,0]
	v_fma_mix_f32 v13, v20, v41, v19 op_sel:[0,1,0] op_sel_hi:[0,1,0]
	s_waitcnt lgkmcnt(4)
	v_add_u32_e32 v6, 0xffffc000, v6
	v_add_u32_e32 v7, 0xffffc000, v7
	v_and_b32_e32 v6, 0x1ffff, v6
	v_and_b32_e32 v7, 0x1ffff, v7
	ds_read_b64 v[24:25], v6 offset:15384
	ds_read_b128 v[26:29], v6 offset:15632
	ds_read_b128 v[30:33], v6 offset:15888
	ds_read_u16 v34, v7 offset:15376
	v_fma_mix_f32 v14, v10, v74, 0 op_sel:[0,0,0] op_sel_hi:[0,1,0]
	v_fma_mix_f32 v61, v10, v44, 0 op_sel:[0,0,0] op_sel_hi:[0,1,0]
	v_fma_mix_f32 v14, v11, v74, v14 op_sel:[0,1,0] op_sel_hi:[0,1,0]
	v_fma_mix_f32 v61, v11, v44, v61 op_sel:[0,1,0] op_sel_hi:[0,1,0]
	v_fma_mix_f32 v14, v12, v75, v14 op_sel:[0,0,0] op_sel_hi:[0,1,0]
	v_fma_mix_f32 v61, v12, v45, v61 op_sel:[0,0,0] op_sel_hi:[0,1,0]
	v_fma_mix_f32 v14, v13, v75, v14 op_sel:[0,1,0] op_sel_hi:[0,1,0]
	v_fma_mix_f32 v16, v10, v72, 0 op_sel:[0,0,0] op_sel_hi:[0,1,0]
	v_fma_mix_f32 v17, v11, v72, 0 op_sel:[0,1,0] op_sel_hi:[0,1,0]
	v_add_f32_dpp v20, v14, v14 quad_perm:[1,0,3,2] row_mask:0xf bank_mask:0xf bound_ctrl:1
	v_fma_mix_f32 v61, v13, v45, v61 op_sel:[0,1,0] op_sel_hi:[0,1,0]
	v_fma_mix_f32 v18, v12, v73, 0 op_sel:[0,0,0] op_sel_hi:[0,1,0]
	v_add_f32_dpp v20, v20, v20 quad_perm:[2,3,0,1] row_mask:0xf bank_mask:0xf bound_ctrl:1
	v_fma_mix_f32 v19, v13, v73, 0 op_sel:[0,1,0] op_sel_hi:[0,1,0]
	v_fma_mix_f32 v16, v82, v78, v16 op_sel:[0,0,0] op_sel_hi:[1,1,0]
	v_add_f32_dpp v20, v20, v20 row_half_mirror row_mask:0xf bank_mask:0xf bound_ctrl:1
	v_fma_mix_f32 v17, v82, v78, v17 op_sel:[0,1,0] op_sel_hi:[1,1,0]
	v_fma_mix_f32 v18, v82, v79, v18 op_sel:[0,0,0] op_sel_hi:[1,1,0]
	v_add_f32_dpp v20, v20, v20 row_mirror row_mask:0xf bank_mask:0xf bound_ctrl:1
	v_fma_mix_f32 v19, v82, v79, v19 op_sel:[0,1,0] op_sel_hi:[1,1,0]
	v_fma_mix_f32 v10, v20, v76, v16 op_sel:[0,0,0] op_sel_hi:[0,1,0]
	v_fma_mix_f32 v11, v20, v76, v17 op_sel:[0,1,0] op_sel_hi:[0,1,0]
	v_fma_mix_f32 v12, v20, v77, v18 op_sel:[0,0,0] op_sel_hi:[0,1,0]
	v_fma_mix_f32 v13, v20, v77, v19 op_sel:[0,1,0] op_sel_hi:[0,1,0]
	s_waitcnt lgkmcnt(4)
	ds_read_b64 v[36:37], v6 offset:14360
	ds_read_b128 v[38:41], v6 offset:14608
	ds_read_b128 v[42:45], v6 offset:14864
	ds_read_u16 v46, v7 offset:14352
	v_fma_mix_f32 v14, v10, v86, 0 op_sel:[0,0,0] op_sel_hi:[0,1,0]
	v_fma_mix_f32 v62, v10, v80, 0 op_sel:[0,0,0] op_sel_hi:[0,1,0]
	v_fma_mix_f32 v14, v11, v86, v14 op_sel:[0,1,0] op_sel_hi:[0,1,0]
	v_fma_mix_f32 v62, v11, v80, v62 op_sel:[0,1,0] op_sel_hi:[0,1,0]
	v_fma_mix_f32 v14, v12, v87, v14 op_sel:[0,0,0] op_sel_hi:[0,1,0]
	v_fma_mix_f32 v62, v12, v81, v62 op_sel:[0,0,0] op_sel_hi:[0,1,0]
	v_fma_mix_f32 v14, v13, v87, v14 op_sel:[0,1,0] op_sel_hi:[0,1,0]
	v_fma_mix_f32 v16, v10, v84, 0 op_sel:[0,0,0] op_sel_hi:[0,1,0]
	v_fma_mix_f32 v17, v11, v84, 0 op_sel:[0,1,0] op_sel_hi:[0,1,0]
	v_add_f32_dpp v20, v14, v14 quad_perm:[1,0,3,2] row_mask:0xf bank_mask:0xf bound_ctrl:1
	v_fma_mix_f32 v62, v13, v81, v62 op_sel:[0,1,0] op_sel_hi:[0,1,0]
	v_fma_mix_f32 v18, v12, v85, 0 op_sel:[0,0,0] op_sel_hi:[0,1,0]
	v_add_f32_dpp v20, v20, v20 quad_perm:[2,3,0,1] row_mask:0xf bank_mask:0xf bound_ctrl:1
	v_fma_mix_f32 v19, v13, v85, 0 op_sel:[0,1,0] op_sel_hi:[0,1,0]
	v_fma_mix_f32 v16, v94, v90, v16 op_sel:[0,0,0] op_sel_hi:[1,1,0]
	v_add_f32_dpp v20, v20, v20 row_half_mirror row_mask:0xf bank_mask:0xf bound_ctrl:1
	v_fma_mix_f32 v17, v94, v90, v17 op_sel:[0,1,0] op_sel_hi:[1,1,0]
	v_fma_mix_f32 v18, v94, v91, v18 op_sel:[0,0,0] op_sel_hi:[1,1,0]
	v_add_f32_dpp v20, v20, v20 row_mirror row_mask:0xf bank_mask:0xf bound_ctrl:1
	v_fma_mix_f32 v19, v94, v91, v19 op_sel:[0,1,0] op_sel_hi:[1,1,0]
	v_fma_mix_f32 v10, v20, v88, v16 op_sel:[0,0,0] op_sel_hi:[0,1,0]
	v_fma_mix_f32 v11, v20, v88, v17 op_sel:[0,1,0] op_sel_hi:[0,1,0]
	v_fma_mix_f32 v12, v20, v89, v18 op_sel:[0,0,0] op_sel_hi:[0,1,0]
	v_fma_mix_f32 v13, v20, v89, v19 op_sel:[0,1,0] op_sel_hi:[0,1,0]
	s_waitcnt lgkmcnt(4)
	s_add_u32 s15, s15, 1
	s_add_u32 s14, s14, 1
	s_cmp_lt_u32 s14, 0x100
	s_cbranch_scc1 .Lrw_blk_d1
; DEVINL u16 f2bf(float a) { return (u16)(pk2(a, 0.f) & 0xffffu); }
; #define RW_STEP2(B) RW_STEP(B, WvA, XA, KrA, vhA, WvB, XB, KrB, vhB); RW_STEP((B) + 1, WvB, XB, KrB, vhB, WvA, XA, KrA, vhA)
; #define RW_STEP4(B) RW_STEP2(B); RW_STEP2((B) + 2)
; template <int DIR>
; DEVINL void rwkv_scan_dir(const Params& p, int task, int lane, int wave) {
;     ...
;     if (st > 0) { const int q0 = st - 16 + seg; yo[(long)(DIR ? (4095 - q0) : q0) * 1024] = f2bf(ykeep); }
;     RW_STEP(1, WvB, XB, KrB, vhB, WvA, XA, KrA, vhA);
;     RW_STEP2(2); RW_STEP4(4); RW_STEP4(8); RW_STEP4(12);
;     RW_STEP(16, WvA, XA, KrA, vhA, WvB, XB, KrB, vhB);
;     { const int q0 = st + seg; yo[(long)(DIR ? (4095 - q0) : q0) * 1024] = f2bf(ykeep); }
;     RW_STEP(17, WvB, XB, KrB, vhB, WvA, XA, KrA, vhA);
;     RW_STEP2(18); RW_STEP4(20); RW_STEP4(24); RW_STEP4(28);
;   }
;   {
;     const float ylast = allred16(ypart);
;     ykeep = (seg == 15) ? ylast : ykeep;
;     const int q0 = 4096 - 16 + seg; yo[(long)(DIR ? (4095 - q0) : q0) * 1024] = f2bf(ykeep);
;   }
	v_fma_mix_f32 v21, v10, v92, 0 op_sel:[0,0,0] op_sel_hi:[0,1,0]
	v_fma_mix_f32 v22, v12, v93, 0 op_sel:[0,0,0] op_sel_hi:[0,1,0]
	v_fma_mix_f32 v21, v11, v92, v21 op_sel:[0,1,0] op_sel_hi:[0,1,0]
	v_fma_mix_f32 v22, v13, v93, v22 op_sel:[0,1,0] op_sel_hi:[0,1,0]
	v_add_f32_e32 v63, v21, v22
	s_nop 1
	v_add_f32_dpp v48, v48, v48 row_ror:8 row_mask:0xf bank_mask:0x3
	v_add_f32_dpp v49, v49, v49 row_ror:8 row_mask:0xf bank_mask:0x3
	v_add_f32_dpp v50, v50, v50 row_ror:8 row_mask:0xf bank_mask:0x3
	v_add_f32_dpp v51, v51, v51 row_ror:8 row_mask:0xf bank_mask:0x3
	v_add_f32_dpp v52, v52, v52 row_ror:8 row_mask:0xf bank_mask:0x3
	v_add_f32_dpp v53, v53, v53 row_ror:8 row_mask:0xf bank_mask:0x3
	v_add_f32_dpp v54, v54, v54 row_ror:8 row_mask:0xf bank_mask:0x3
	v_add_f32_dpp v55, v55, v55 row_ror:8 row_mask:0xf bank_mask:0x3
	v_add_f32_dpp v48, v56, v56 row_ror:8 row_mask:0xf bank_mask:0xc
	v_add_f32_dpp v49, v57, v57 row_ror:8 row_mask:0xf bank_mask:0xc
	v_add_f32_dpp v50, v58, v58 row_ror:8 row_mask:0xf bank_mask:0xc
	v_add_f32_dpp v51, v59, v59 row_ror:8 row_mask:0xf bank_mask:0xc
	v_add_f32_dpp v52, v60, v60 row_ror:8 row_mask:0xf bank_mask:0xc
	v_add_f32_dpp v53, v61, v61 row_ror:8 row_mask:0xf bank_mask:0xc
	v_add_f32_dpp v54, v62, v62 row_ror:8 row_mask:0xf bank_mask:0xc
	v_add_f32_dpp v55, v63, v63 row_ror:8 row_mask:0xf bank_mask:0xc
	v_add_f32_dpp v48, v48, v48 row_ror:12 row_mask:0xf bank_mask:0x5
	v_add_f32_dpp v49, v49, v49 row_ror:12 row_mask:0xf bank_mask:0x5
	v_add_f32_dpp v50, v50, v50 row_ror:12 row_mask:0xf bank_mask:0x5
	v_add_f32_dpp v51, v51, v51 row_ror:12 row_mask:0xf bank_mask:0x5
	v_add_f32_dpp v48, v52, v52 row_ror:4 row_mask:0xf bank_mask:0xa
	v_add_f32_dpp v49, v53, v53 row_ror:4 row_mask:0xf bank_mask:0xa
	v_add_f32_dpp v50, v54, v54 row_ror:4 row_mask:0xf bank_mask:0xa
	v_add_f32_dpp v51, v55, v55 row_ror:4 row_mask:0xf bank_mask:0xa
	v_add_f32_dpp v64, v48, v48 quad_perm:[2,3,0,1] row_mask:0xf bank_mask:0xf bound_ctrl:1
	v_add_f32_dpp v65, v50, v50 quad_perm:[2,3,0,1] row_mask:0xf bank_mask:0xf bound_ctrl:1
	v_cndmask_b32_e64 v56, v64, v65, s[50:51]
	v_add_f32_dpp v64, v49, v49 quad_perm:[2,3,0,1] row_mask:0xf bank_mask:0xf bound_ctrl:1
	v_add_f32_dpp v65, v51, v51 quad_perm:[2,3,0,1] row_mask:0xf bank_mask:0xf bound_ctrl:1
	v_cndmask_b32_e64 v57, v64, v65, s[50:51]
	v_add_f32_dpp v64, v56, v56 quad_perm:[1,0,3,2] row_mask:0xf bank_mask:0xf bound_ctrl:1
	s_nop 0
	v_add_f32_dpp v65, v57, v57 quad_perm:[1,0,3,2] row_mask:0xf bank_mask:0xf bound_ctrl:1
	v_cndmask_b32_e64 v66, v64, v65, s[48:49]
	v_cvt_pk_bf16_f32 v66, v66, v66
	global_store_short v8, v66, s[12:13]
	s_sub_u32 s12, s12, 0x8000
	s_subb_u32 s13, s13, 0
